# removed per-segment s_setprio from the four GEMM K-loops (on top of trimmed waits, saddr LDS-DMA, straight-line row scales)
# speedup vs baseline: 1.0068x; 1.0054x over previous
; #define PG8_STAGE(bufoff, gbase, voff) do { _Pragma("unroll") for (int _i = 0; _i < 2; ++_i) \
;         __builtin_amdgcn_global_load_lds((const unsigned*)((const char*)(gbase) + (voff)[_i]), (PG8_LAS unsigned*)(lds + (bufoff) + ldsw + _i * 8192), 16, 0, 0); } while (0)
; #define PG8_LDA(dst, b, h) do { _Pragma("unroll") for (int m = 0; m < 4; ++m) _Pragma("unroll") for (int k = 0; k < 2; ++k) dst[m][k] = *(const PG8_LAS bf16x8*)(lds + PG8_SA(b, h) + aoff + m * 2048 + k * 1024); } while (0)
; #define PG8_LDB(dst, b, h) do { _Pragma("unroll") for (int n = 0; n < 2; ++n) _Pragma("unroll") for (int k = 0; k < 2; ++k) dst[n][k] = *(const PG8_LAS bf16x8*)(lds + PG8_SB(b, h) + boff + n * 2048 + k * 1024); } while (0)
; #define PG8_MMA(ai, bj, At, Bt) do { __builtin_amdgcn_s_setprio(1); _Pragma("unroll") for (int m = 0; m < 4; ++m) _Pragma("unroll") for (int n = 0; n < 2; ++n) _Pragma("unroll") for (int k = 0; k < 2; ++k) \
;         acc[ai][bj][m][n] = __builtin_amdgcn_mfma_f32_16x16x32_bf16(Bt[n][k], At[m][k], acc[ai][bj][m][n], 0, 0, 0); __builtin_amdgcn_s_setprio(0); } while (0)
; #define PG8_WAIT_V(n) asm volatile("s_waitcnt vmcnt(" #n ")" ::: "memory")
; #define PG8_WAIT_L(n) asm volatile("s_waitcnt lgkmcnt(" #n ")" ::: "memory")
; template <class Epi, class Sched, bool ALIGN_EPI = false, bool SP2 = false>
; __device__ __forceinline__ void gemm_phase(PG8_LAS unsigned char* lds, const Gemm g, const Sched& S, const Epi& E) {
;     ...
;             const bool last = (t == nt - 2);
;             const char* a1 = cA + (size_t)(t + 1) * kstep;
;             const char* a2 = last ? nA : cA + (size_t)(t + 2) * kstep; const char* b2 = last ? nB : cB + (size_t)(t + 2) * kstep;
;             const char* a3 = a2 + kstep; const char* b3 = b2 + kstep;
;             if (last && has_next) S.a_ready(nxt);
;             if constexpr (SP2) {
;             PG8_LDB(B0, 0, 0); PG8_LDB(B1, 0, 1); PG8_SCHED; PG8_LDA(At, 0, 0); PG8_STAGE(PG8_SA(1, 1), a1 + hstep, voffA);
;             PG8_WAIT_V(8); PG8_WAIT_L(0); PG8_BAR; PG8_MMA(0, 0, At, B0); PG8_MMA(0, 1, At, B1); PG8_BAR; PG8_SCHED;
;             PG8_LDA(At, 0, 1); PG8_STAGE(PG8_SB(0, 0), b2, voffB); PG8_STAGE(PG8_SB(0, 1), b2 + hstep, voffB); PG8_STAGE(PG8_SA(0, 0), a2, voffA);
;             PG8_WAIT_V(8); PG8_WAIT_L(0); PG8_BAR; PG8_MMA(1, 0, At, B0); PG8_MMA(1, 1, At, B1); PG8_BAR; PG8_SCHED;
.LBB0_65:
	s_add_u32 s20, s18, 0xfffc0080
	s_addc_u32 s21, s19, -1
	s_cmp_eq_u32 s49, 12
	s_cselect_b32 s23, s11, s21
	s_cselect_b32 s22, s45, s20
	s_cselect_b32 s21, s9, s48
	s_cselect_b32 s20, s46, s47
	ds_read_b128 v[146:149], v216
	ds_read_b128 v[150:153], v216 offset:1024
	ds_read_b128 v[154:157], v216 offset:2048
	ds_read_b128 v[158:161], v216 offset:3072
	ds_read_b128 v[162:165], v216 offset:16384
	ds_read_b128 v[166:169], v216 offset:17408
	ds_read_b128 v[170:173], v216 offset:18432
	ds_read_b128 v[174:177], v216 offset:19456
	s_add_i32 m0, s34, 0xc000
	ds_read_b128 v[178:181], v144
	ds_read_b128 v[188:191], v144 offset:1024
	ds_read_b128 v[192:195], v144 offset:2048
	ds_read_b128 v[196:199], v144 offset:3072
	ds_read_b128 v[200:203], v144 offset:4096
	ds_read_b128 v[204:207], v144 offset:5120
	ds_read_b128 v[208:211], v144 offset:6144
	ds_read_b128 v[212:215], v144 offset:7168
	global_load_lds_dwordx4 v136, s[18:19]
	s_add_i32 m0, s34, 0xe000
	s_add_i32 s50, s33, 0x10000
	global_load_lds_dwordx4 v138, s[18:19]
	s_waitcnt vmcnt(8)
	s_waitcnt lgkmcnt(0)
	s_barrier
	v_mfma_f32_16x16x32_bf16 v[126:129], v[146:149], v[178:181], v[126:129]
	v_mfma_f32_16x16x32_bf16 v[118:121], v[154:157], v[178:181], v[118:121]
	v_mfma_f32_16x16x32_bf16 v[110:113], v[146:149], v[192:195], v[110:113]
	v_mfma_f32_16x16x32_bf16 v[102:105], v[154:157], v[192:195], v[102:105]
	v_mfma_f32_16x16x32_bf16 v[94:97], v[146:149], v[200:203], v[94:97]
	v_mfma_f32_16x16x32_bf16 v[86:89], v[154:157], v[200:203], v[86:89]
	v_mfma_f32_16x16x32_bf16 v[78:81], v[146:149], v[208:211], v[78:81]
	v_mfma_f32_16x16x32_bf16 v[70:73], v[154:157], v[208:211], v[70:73]
	v_mfma_f32_16x16x32_bf16 v[126:129], v[150:153], v[188:191], v[126:129]
	v_mfma_f32_16x16x32_bf16 v[118:121], v[158:161], v[188:191], v[118:121]
	v_mfma_f32_16x16x32_bf16 v[110:113], v[150:153], v[196:199], v[110:113]
	v_mfma_f32_16x16x32_bf16 v[102:105], v[158:161], v[196:199], v[102:105]
	v_mfma_f32_16x16x32_bf16 v[94:97], v[150:153], v[204:207], v[94:97]
	v_mfma_f32_16x16x32_bf16 v[86:89], v[158:161], v[204:207], v[86:89]
	v_mfma_f32_16x16x32_bf16 v[78:81], v[150:153], v[212:215], v[78:81]
	v_mfma_f32_16x16x32_bf16 v[70:73], v[158:161], v[212:215], v[70:73]
	v_mfma_f32_16x16x32_bf16 v[122:125], v[162:165], v[178:181], v[122:125]
	v_mfma_f32_16x16x32_bf16 v[114:117], v[170:173], v[178:181], v[114:117]
	v_mfma_f32_16x16x32_bf16 v[106:109], v[162:165], v[192:195], v[106:109]
	v_mfma_f32_16x16x32_bf16 v[98:101], v[170:173], v[192:195], v[98:101]
	v_mfma_f32_16x16x32_bf16 v[90:93], v[162:165], v[200:203], v[90:93]
	v_mfma_f32_16x16x32_bf16 v[82:85], v[170:173], v[200:203], v[82:85]
	v_mfma_f32_16x16x32_bf16 v[74:77], v[162:165], v[208:211], v[74:77]
	v_mfma_f32_16x16x32_bf16 v[66:69], v[170:173], v[208:211], v[66:69]
	v_mfma_f32_16x16x32_bf16 v[122:125], v[166:169], v[188:191], v[122:125]
	v_mfma_f32_16x16x32_bf16 v[114:117], v[174:177], v[188:191], v[114:117]
	v_mfma_f32_16x16x32_bf16 v[106:109], v[166:169], v[196:199], v[106:109]
	v_mfma_f32_16x16x32_bf16 v[98:101], v[174:177], v[196:199], v[98:101]
	v_mfma_f32_16x16x32_bf16 v[90:93], v[166:169], v[204:207], v[90:93]
	v_mfma_f32_16x16x32_bf16 v[82:85], v[174:177], v[204:207], v[82:85]
	v_mfma_f32_16x16x32_bf16 v[74:77], v[166:169], v[212:215], v[74:77]
	v_mfma_f32_16x16x32_bf16 v[66:69], v[174:177], v[212:215], v[66:69]
	s_barrier
	s_mov_b32 m0, s50
	ds_read_b128 v[178:181], v144 offset:16384
	ds_read_b128 v[188:191], v144 offset:17408
	ds_read_b128 v[192:195], v144 offset:18432
	ds_read_b128 v[196:199], v144 offset:19456
	ds_read_b128 v[200:203], v144 offset:20480
	ds_read_b128 v[204:207], v144 offset:21504
	ds_read_b128 v[208:211], v144 offset:22528
	ds_read_b128 v[212:215], v144 offset:23552
	global_load_lds_dwordx4 v64, s[20:21]
	s_add_i32 m0, s50, 0x2000
	s_add_u32 s98, s20, 0x40000
	s_addc_u32 s99, s21, 0
	global_load_lds_dwordx4 v130, s[20:21]
	s_add_i32 m0, s33, 0x14000
	s_nop 0
	global_load_lds_dwordx4 v64, s[98:99]
	s_add_i32 m0, s33, 0x16000
	s_nop 0
	global_load_lds_dwordx4 v130, s[98:99]
	s_mov_b32 m0, s34
	s_nop 0
	global_load_lds_dwordx4 v134, s[22:23]
	s_mov_b32 m0, s35
	s_nop 0
	global_load_lds_dwordx4 v132, s[22:23]
	s_waitcnt vmcnt(8)
	s_waitcnt lgkmcnt(0)
	s_barrier
	v_mfma_f32_16x16x32_bf16 v[60:63], v[146:149], v[178:181], v[60:63]
	v_mfma_f32_16x16x32_bf16 v[52:55], v[154:157], v[178:181], v[52:55]
	v_mfma_f32_16x16x32_bf16 v[44:47], v[146:149], v[192:195], v[44:47]
	v_mfma_f32_16x16x32_bf16 v[36:39], v[154:157], v[192:195], v[36:39]
	v_mfma_f32_16x16x32_bf16 v[28:31], v[146:149], v[200:203], v[28:31]
	v_mfma_f32_16x16x32_bf16 v[20:23], v[154:157], v[200:203], v[20:23]
	v_mfma_f32_16x16x32_bf16 v[12:15], v[146:149], v[208:211], v[12:15]
	v_mfma_f32_16x16x32_bf16 v[4:7], v[154:157], v[208:211], v[4:7]
	v_mfma_f32_16x16x32_bf16 v[60:63], v[150:153], v[188:191], v[60:63]
	v_mfma_f32_16x16x32_bf16 v[52:55], v[158:161], v[188:191], v[52:55]
	v_mfma_f32_16x16x32_bf16 v[44:47], v[150:153], v[196:199], v[44:47]
	v_mfma_f32_16x16x32_bf16 v[36:39], v[158:161], v[196:199], v[36:39]
	v_mfma_f32_16x16x32_bf16 v[28:31], v[150:153], v[204:207], v[28:31]
	v_mfma_f32_16x16x32_bf16 v[20:23], v[158:161], v[204:207], v[20:23]
	v_mfma_f32_16x16x32_bf16 v[12:15], v[150:153], v[212:215], v[12:15]
	v_mfma_f32_16x16x32_bf16 v[4:7], v[158:161], v[212:215], v[4:7]
	v_mfma_f32_16x16x32_bf16 v[56:59], v[162:165], v[178:181], v[56:59]
	v_mfma_f32_16x16x32_bf16 v[48:51], v[170:173], v[178:181], v[48:51]
	v_mfma_f32_16x16x32_bf16 v[40:43], v[162:165], v[192:195], v[40:43]
	v_mfma_f32_16x16x32_bf16 v[32:35], v[170:173], v[192:195], v[32:35]
	v_mfma_f32_16x16x32_bf16 v[24:27], v[162:165], v[200:203], v[24:27]
	v_mfma_f32_16x16x32_bf16 v[16:19], v[170:173], v[200:203], v[16:19]
	v_mfma_f32_16x16x32_bf16 v[8:11], v[162:165], v[208:211], v[8:11]
	v_mfma_f32_16x16x32_bf16 v[0:3], v[170:173], v[208:211], v[0:3]
	v_mfma_f32_16x16x32_bf16 v[56:59], v[166:169], v[188:191], v[56:59]
	v_mfma_f32_16x16x32_bf16 v[48:51], v[174:177], v[188:191], v[48:51]
	v_mfma_f32_16x16x32_bf16 v[40:43], v[166:169], v[196:199], v[40:43]
	v_mfma_f32_16x16x32_bf16 v[32:35], v[174:177], v[196:199], v[32:35]
	v_mfma_f32_16x16x32_bf16 v[24:27], v[166:169], v[204:207], v[24:27]
	v_mfma_f32_16x16x32_bf16 v[16:19], v[174:177], v[204:207], v[16:19]
	v_mfma_f32_16x16x32_bf16 v[8:11], v[166:169], v[212:215], v[8:11]
	v_mfma_f32_16x16x32_bf16 v[0:3], v[174:177], v[212:215], v[0:3]
	s_barrier
; #define PG8_STAGE(bufoff, gbase, voff) do { _Pragma("unroll") for (int _i = 0; _i < 2; ++_i) \
;         __builtin_amdgcn_global_load_lds((const unsigned*)((const char*)(gbase) + (voff)[_i]), (PG8_LAS unsigned*)(lds + (bufoff) + ldsw + _i * 8192), 16, 0, 0); } while (0)
; #define PG8_LDA(dst, b, h) do { _Pragma("unroll") for (int m = 0; m < 4; ++m) _Pragma("unroll") for (int k = 0; k < 2; ++k) dst[m][k] = *(const PG8_LAS bf16x8*)(lds + PG8_SA(b, h) + aoff + m * 2048 + k * 1024); } while (0)
; #define PG8_LDB(dst, b, h) do { _Pragma("unroll") for (int n = 0; n < 2; ++n) _Pragma("unroll") for (int k = 0; k < 2; ++k) dst[n][k] = *(const PG8_LAS bf16x8*)(lds + PG8_SB(b, h) + boff + n * 2048 + k * 1024); } while (0)
; #define PG8_MMA(ai, bj, At, Bt) do { __builtin_amdgcn_s_setprio(1); _Pragma("unroll") for (int m = 0; m < 4; ++m) _Pragma("unroll") for (int n = 0; n < 2; ++n) _Pragma("unroll") for (int k = 0; k < 2; ++k) \
;         acc[ai][bj][m][n] = __builtin_amdgcn_mfma_f32_16x16x32_bf16(Bt[n][k], At[m][k], acc[ai][bj][m][n], 0, 0, 0); __builtin_amdgcn_s_setprio(0); } while (0)
; #define PG8_WAIT_V(n) asm volatile("s_waitcnt vmcnt(" #n ")" ::: "memory")
; #define PG8_WAIT_L(n) asm volatile("s_waitcnt lgkmcnt(" #n ")" ::: "memory")
; #define PG8_BAR __builtin_amdgcn_s_barrier()
; #define PG8_SCHED __builtin_amdgcn_sched_barrier(0)
; template <class Epi, class Sched, bool ALIGN_EPI = false, bool SP2 = false>
; __device__ __forceinline__ void gemm_phase(PG8_LAS unsigned char* lds, const Gemm g, const Sched& S, const Epi& E) {
;     ...
;             PG8_LDB(B0, 1, 0); PG8_LDB(B1, 1, 1); PG8_SCHED; PG8_LDA(At, 1, 0); PG8_STAGE(PG8_SA(0, 1), a2 + hstep, voffA);
;             PG8_WAIT_V(8); PG8_WAIT_L(0); PG8_BAR; PG8_MMA(0, 0, At, B0); PG8_MMA(0, 1, At, B1); PG8_BAR; PG8_SCHED;
;             PG8_LDA(At, 1, 1); PG8_STAGE(PG8_SB(1, 0), b3, voffB); PG8_STAGE(PG8_SB(1, 1), b3 + hstep, voffB); PG8_STAGE(PG8_SA(1, 0), a3, voffA);
;             PG8_WAIT_V(8); PG8_WAIT_L(0); PG8_BAR; PG8_MMA(1, 0, At, B0); PG8_MMA(1, 1, At, B1); PG8_BAR; PG8_SCHED;
	ds_read_b128 v[146:149], v216 offset:32768
	ds_read_b128 v[150:153], v216 offset:33792
	ds_read_b128 v[154:157], v216 offset:34816
	ds_read_b128 v[158:161], v216 offset:35840
	ds_read_b128 v[162:165], v216 offset:49152
	ds_read_b128 v[166:169], v216 offset:50176
	ds_read_b128 v[170:173], v216 offset:51200
	ds_read_b128 v[174:177], v216 offset:52224
	s_add_u32 s22, s22, 0x40000
	s_addc_u32 s23, s23, 0
	s_mov_b32 m0, s36
	ds_read_b128 v[178:181], v144 offset:32768
	ds_read_b128 v[188:191], v144 offset:33792
	ds_read_b128 v[192:195], v144 offset:34816
	ds_read_b128 v[196:199], v144 offset:35840
	ds_read_b128 v[200:203], v144 offset:36864
	ds_read_b128 v[204:207], v144 offset:37888
	ds_read_b128 v[208:211], v144 offset:38912
	ds_read_b128 v[212:215], v144 offset:39936
	global_load_lds_dwordx4 v134, s[22:23]
	s_mov_b32 m0, s37
	s_add_u32 s98, s20, 0x80
	s_addc_u32 s99, s21, 0
	global_load_lds_dwordx4 v132, s[22:23]
	s_waitcnt vmcnt(8)
	s_waitcnt lgkmcnt(0)
	s_barrier
	v_mfma_f32_16x16x32_bf16 v[126:129], v[146:149], v[178:181], v[126:129]
	v_mfma_f32_16x16x32_bf16 v[118:121], v[154:157], v[178:181], v[118:121]
	v_mfma_f32_16x16x32_bf16 v[110:113], v[146:149], v[192:195], v[110:113]
	v_mfma_f32_16x16x32_bf16 v[102:105], v[154:157], v[192:195], v[102:105]
	v_mfma_f32_16x16x32_bf16 v[94:97], v[146:149], v[200:203], v[94:97]
	v_mfma_f32_16x16x32_bf16 v[86:89], v[154:157], v[200:203], v[86:89]
	v_mfma_f32_16x16x32_bf16 v[78:81], v[146:149], v[208:211], v[78:81]
	v_mfma_f32_16x16x32_bf16 v[70:73], v[154:157], v[208:211], v[70:73]
	v_mfma_f32_16x16x32_bf16 v[126:129], v[150:153], v[188:191], v[126:129]
	v_mfma_f32_16x16x32_bf16 v[118:121], v[158:161], v[188:191], v[118:121]
	v_mfma_f32_16x16x32_bf16 v[110:113], v[150:153], v[196:199], v[110:113]
	v_mfma_f32_16x16x32_bf16 v[102:105], v[158:161], v[196:199], v[102:105]
	v_mfma_f32_16x16x32_bf16 v[94:97], v[150:153], v[204:207], v[94:97]
	v_mfma_f32_16x16x32_bf16 v[86:89], v[158:161], v[204:207], v[86:89]
	v_mfma_f32_16x16x32_bf16 v[78:81], v[150:153], v[212:215], v[78:81]
	v_mfma_f32_16x16x32_bf16 v[70:73], v[158:161], v[212:215], v[70:73]
	v_mfma_f32_16x16x32_bf16 v[122:125], v[162:165], v[178:181], v[122:125]
	v_mfma_f32_16x16x32_bf16 v[114:117], v[170:173], v[178:181], v[114:117]
	v_mfma_f32_16x16x32_bf16 v[106:109], v[162:165], v[192:195], v[106:109]
	v_mfma_f32_16x16x32_bf16 v[98:101], v[170:173], v[192:195], v[98:101]
	v_mfma_f32_16x16x32_bf16 v[90:93], v[162:165], v[200:203], v[90:93]
	v_mfma_f32_16x16x32_bf16 v[82:85], v[170:173], v[200:203], v[82:85]
	v_mfma_f32_16x16x32_bf16 v[74:77], v[162:165], v[208:211], v[74:77]
	v_mfma_f32_16x16x32_bf16 v[66:69], v[170:173], v[208:211], v[66:69]
	v_mfma_f32_16x16x32_bf16 v[122:125], v[166:169], v[188:191], v[122:125]
	v_mfma_f32_16x16x32_bf16 v[114:117], v[174:177], v[188:191], v[114:117]
	v_mfma_f32_16x16x32_bf16 v[106:109], v[166:169], v[196:199], v[106:109]
	v_mfma_f32_16x16x32_bf16 v[98:101], v[174:177], v[196:199], v[98:101]
	v_mfma_f32_16x16x32_bf16 v[90:93], v[166:169], v[204:207], v[90:93]
	v_mfma_f32_16x16x32_bf16 v[82:85], v[174:177], v[204:207], v[82:85]
	v_mfma_f32_16x16x32_bf16 v[74:77], v[166:169], v[212:215], v[74:77]
	v_mfma_f32_16x16x32_bf16 v[66:69], v[174:177], v[212:215], v[66:69]
	s_barrier
	s_add_i32 m0, s33, 0x18000
	ds_read_b128 v[178:181], v144 offset:49152
	ds_read_b128 v[188:191], v144 offset:50176
	ds_read_b128 v[192:195], v144 offset:51200
	ds_read_b128 v[196:199], v144 offset:52224
	ds_read_b128 v[200:203], v144 offset:53248
	ds_read_b128 v[204:207], v144 offset:54272
	ds_read_b128 v[208:211], v144 offset:55296
	ds_read_b128 v[212:215], v144 offset:56320
	global_load_lds_dwordx4 v64, s[98:99]
	s_add_i32 m0, s33, 0x1a000
	s_add_u32 s20, s20, 0x40080
	s_addc_u32 s21, s21, 0
	global_load_lds_dwordx4 v130, s[98:99]
	s_add_i32 m0, s33, 0x1c000
	s_add_u32 s22, s22, 0xfffc0080
	s_addc_u32 s23, s23, -1
	global_load_lds_dwordx4 v64, s[20:21]
	s_add_i32 m0, s33, 0x1e000
	s_nop 0
	global_load_lds_dwordx4 v130, s[20:21]
	s_mov_b32 m0, s38
	s_nop 0
	global_load_lds_dwordx4 v134, s[22:23]
	s_mov_b32 m0, s39
	s_nop 0
	global_load_lds_dwordx4 v132, s[22:23]
	s_waitcnt vmcnt(8)
	s_waitcnt lgkmcnt(0)
	s_barrier
	v_mfma_f32_16x16x32_bf16 v[60:63], v[146:149], v[178:181], v[60:63]
	v_mfma_f32_16x16x32_bf16 v[52:55], v[154:157], v[178:181], v[52:55]
	v_mfma_f32_16x16x32_bf16 v[44:47], v[146:149], v[192:195], v[44:47]
	v_mfma_f32_16x16x32_bf16 v[36:39], v[154:157], v[192:195], v[36:39]
	v_mfma_f32_16x16x32_bf16 v[28:31], v[146:149], v[200:203], v[28:31]
	v_mfma_f32_16x16x32_bf16 v[20:23], v[154:157], v[200:203], v[20:23]
	v_mfma_f32_16x16x32_bf16 v[12:15], v[146:149], v[208:211], v[12:15]
	v_mfma_f32_16x16x32_bf16 v[4:7], v[154:157], v[208:211], v[4:7]
	v_mfma_f32_16x16x32_bf16 v[60:63], v[150:153], v[188:191], v[60:63]
	v_mfma_f32_16x16x32_bf16 v[52:55], v[158:161], v[188:191], v[52:55]
	v_mfma_f32_16x16x32_bf16 v[44:47], v[150:153], v[196:199], v[44:47]
	v_mfma_f32_16x16x32_bf16 v[36:39], v[158:161], v[196:199], v[36:39]
	v_mfma_f32_16x16x32_bf16 v[28:31], v[150:153], v[204:207], v[28:31]
	v_mfma_f32_16x16x32_bf16 v[20:23], v[158:161], v[204:207], v[20:23]
	v_mfma_f32_16x16x32_bf16 v[12:15], v[150:153], v[212:215], v[12:15]
	v_mfma_f32_16x16x32_bf16 v[4:7], v[158:161], v[212:215], v[4:7]
	v_mfma_f32_16x16x32_bf16 v[56:59], v[162:165], v[178:181], v[56:59]
	v_mfma_f32_16x16x32_bf16 v[48:51], v[170:173], v[178:181], v[48:51]
	v_mfma_f32_16x16x32_bf16 v[40:43], v[162:165], v[192:195], v[40:43]
	v_mfma_f32_16x16x32_bf16 v[32:35], v[170:173], v[192:195], v[32:35]
	v_mfma_f32_16x16x32_bf16 v[24:27], v[162:165], v[200:203], v[24:27]
	v_mfma_f32_16x16x32_bf16 v[16:19], v[170:173], v[200:203], v[16:19]
	v_mfma_f32_16x16x32_bf16 v[8:11], v[162:165], v[208:211], v[8:11]
	v_mfma_f32_16x16x32_bf16 v[0:3], v[170:173], v[208:211], v[0:3]
	v_mfma_f32_16x16x32_bf16 v[56:59], v[166:169], v[188:191], v[56:59]
	v_mfma_f32_16x16x32_bf16 v[48:51], v[174:177], v[188:191], v[48:51]
	v_mfma_f32_16x16x32_bf16 v[40:43], v[166:169], v[196:199], v[40:43]
	v_mfma_f32_16x16x32_bf16 v[32:35], v[174:177], v[196:199], v[32:35]
	v_mfma_f32_16x16x32_bf16 v[24:27], v[166:169], v[204:207], v[24:27]
	v_mfma_f32_16x16x32_bf16 v[16:19], v[174:177], v[204:207], v[16:19]
	v_mfma_f32_16x16x32_bf16 v[8:11], v[166:169], v[212:215], v[8:11]
	v_mfma_f32_16x16x32_bf16 v[0:3], v[174:177], v[212:215], v[0:3]
	s_barrier
	s_add_i32 s49, s49, 2
	s_add_u32 s18, s18, 0x100
	s_addc_u32 s19, s19, 0
	s_add_u32 s47, s47, 0x100
	s_addc_u32 s48, s48, 0
	s_cmp_gt_u32 s49, 13
	s_cbranch_scc0 .LBB0_65
	s_and_b64 vcc, exec, s[6:7]
	s_cbranch_vccz .LBB0_68
	s_barrier

; #define PG8_STAGE(bufoff, gbase, voff) do { _Pragma("unroll") for (int _i = 0; _i < 2; ++_i) \
;         __builtin_amdgcn_global_load_lds((const unsigned*)((const char*)(gbase) + (voff)[_i]), (PG8_LAS unsigned*)(lds + (bufoff) + ldsw + _i * 8192), 16, 0, 0); } while (0)
; #define PG8_LDA(dst, b, h) do { _Pragma("unroll") for (int m = 0; m < 4; ++m) _Pragma("unroll") for (int k = 0; k < 2; ++k) dst[m][k] = *(const PG8_LAS bf16x8*)(lds + PG8_SA(b, h) + aoff + m * 2048 + k * 1024); } while (0)
; #define PG8_LDB(dst, b, h) do { _Pragma("unroll") for (int n = 0; n < 2; ++n) _Pragma("unroll") for (int k = 0; k < 2; ++k) dst[n][k] = *(const PG8_LAS bf16x8*)(lds + PG8_SB(b, h) + boff + n * 2048 + k * 1024); } while (0)
; #define PG8_MMA(ai, bj, At, Bt) do { __builtin_amdgcn_s_setprio(1); _Pragma("unroll") for (int m = 0; m < 4; ++m) _Pragma("unroll") for (int n = 0; n < 2; ++n) _Pragma("unroll") for (int k = 0; k < 2; ++k) \
;         acc[ai][bj][m][n] = __builtin_amdgcn_mfma_f32_16x16x32_bf16(Bt[n][k], At[m][k], acc[ai][bj][m][n], 0, 0, 0); __builtin_amdgcn_s_setprio(0); } while (0)
; #define PG8_WAIT_V(n) asm volatile("s_waitcnt vmcnt(" #n ")" ::: "memory")
; #define PG8_WAIT_L(n) asm volatile("s_waitcnt lgkmcnt(" #n ")" ::: "memory")
; template <class Epi, class Sched, bool ALIGN_EPI = false, bool SP2 = false>
; __device__ __forceinline__ void gemm_phase(PG8_LAS unsigned char* lds, const Gemm g, const Sched& S, const Epi& E) {
;     ...
;             const bool last = (t == nt - 2);
;             const char* a1 = cA + (size_t)(t + 1) * kstep;
;             const char* a2 = last ? nA : cA + (size_t)(t + 2) * kstep; const char* b2 = last ? nB : cB + (size_t)(t + 2) * kstep;
;             const char* a3 = a2 + kstep; const char* b3 = b2 + kstep;
;             if (last && has_next) S.a_ready(nxt);
;             if constexpr (SP2) {
;             PG8_LDB(B0, 0, 0); PG8_LDB(B1, 0, 1); PG8_SCHED; PG8_LDA(At, 0, 0); PG8_STAGE(PG8_SA(1, 1), a1 + hstep, voffA);
;             PG8_WAIT_V(8); PG8_WAIT_L(0); PG8_BAR; PG8_MMA(0, 0, At, B0); PG8_MMA(0, 1, At, B1); PG8_BAR; PG8_SCHED;
;             PG8_LDA(At, 0, 1); PG8_STAGE(PG8_SB(0, 0), b2, voffB); PG8_STAGE(PG8_SB(0, 1), b2 + hstep, voffB); PG8_STAGE(PG8_SA(0, 0), a2, voffA);
;             PG8_WAIT_V(8); PG8_WAIT_L(0); PG8_BAR; PG8_MMA(1, 0, At, B0); PG8_MMA(1, 1, At, B1); PG8_BAR; PG8_SCHED;
.LBB0_97:
	s_add_i32 s46, s20, 2
	s_add_u32 s47, s18, 0x80
	s_addc_u32 s21, s19, 0
	s_add_i32 s54, 0, 0x10000
	s_cmp_eq_u32 s41, s20
	s_cselect_b32 s21, s1, s21
	s_cselect_b32 s20, s0, s47
	v_add_u32_e32 v64, s54, v231
	s_cselect_b32 s53, s17, s23
	s_cselect_b32 s52, s16, s22
	s_add_i32 s47, 0, 0x14000
	ds_read_b128 v[56:59], v64
	ds_read_b128 v[72:75], v64 offset:1024
	ds_read_b128 v[76:79], v64 offset:2048
	ds_read_b128 v[80:83], v64 offset:3072
	v_add_u32_e32 v64, s47, v231
	ds_read_b128 v[84:87], v64
	ds_read_b128 v[88:91], v64 offset:1024
	ds_read_b128 v[92:95], v64 offset:2048
	ds_read_b128 v[100:103], v64 offset:3072
	v_lshl_add_u64 v[66:67], s[18:19], 0, v[196:197]
	s_add_i32 m0, s33, 0xc000
	ds_read_b128 v[116:119], v233
	ds_read_b128 v[120:123], v233 offset:1024
	ds_read_b128 v[140:143], v233 offset:2048
	ds_read_b128 v[144:147], v233 offset:3072
	ds_read_b128 v[180:183], v233 offset:4096
	ds_read_b128 v[200:203], v233 offset:5120
	ds_read_b128 v[204:207], v233 offset:6144
	ds_read_b128 v[208:211], v233 offset:7168
	global_load_lds_dwordx4 v[66:67], off
	v_lshl_add_u64 v[66:67], s[18:19], 0, v[198:199]
	s_add_i32 m0, s33, 0xe000
	s_nop 0
	global_load_lds_dwordx4 v[66:67], off
	s_waitcnt vmcnt(8)
	s_waitcnt lgkmcnt(0)
	s_barrier
	v_mfma_f32_16x16x32_bf16 v[176:179], v[56:59], v[116:119], v[176:179]
	v_mfma_f32_16x16x32_bf16 v[172:175], v[76:79], v[116:119], v[172:175]
	v_mfma_f32_16x16x32_bf16 v[160:163], v[56:59], v[140:143], v[160:163]
	v_mfma_f32_16x16x32_bf16 v[156:159], v[76:79], v[140:143], v[156:159]
	v_mfma_f32_16x16x32_bf16 v[136:139], v[56:59], v[180:183], v[136:139]
	v_mfma_f32_16x16x32_bf16 v[132:135], v[76:79], v[180:183], v[132:135]
	v_mfma_f32_16x16x32_bf16 v[112:115], v[56:59], v[204:207], v[112:115]
	v_mfma_f32_16x16x32_bf16 v[108:111], v[76:79], v[204:207], v[108:111]
	v_mfma_f32_16x16x32_bf16 v[176:179], v[72:75], v[120:123], v[176:179]
	v_mfma_f32_16x16x32_bf16 v[172:175], v[80:83], v[120:123], v[172:175]
	v_mfma_f32_16x16x32_bf16 v[160:163], v[72:75], v[144:147], v[160:163]
	v_mfma_f32_16x16x32_bf16 v[156:159], v[80:83], v[144:147], v[156:159]
	v_mfma_f32_16x16x32_bf16 v[136:139], v[72:75], v[200:203], v[136:139]
	v_mfma_f32_16x16x32_bf16 v[132:135], v[80:83], v[200:203], v[132:135]
	v_mfma_f32_16x16x32_bf16 v[112:115], v[72:75], v[208:211], v[112:115]
	v_mfma_f32_16x16x32_bf16 v[108:111], v[80:83], v[208:211], v[108:111]
	v_mfma_f32_16x16x32_bf16 v[168:171], v[84:87], v[116:119], v[168:171]
	v_mfma_f32_16x16x32_bf16 v[116:119], v[92:95], v[116:119], v[164:167]
	v_mfma_f32_16x16x32_bf16 v[128:131], v[84:87], v[180:183], v[128:131]
	v_mfma_f32_16x16x32_bf16 v[124:127], v[92:95], v[180:183], v[124:127]
	v_mfma_f32_16x16x32_bf16 v[104:107], v[84:87], v[204:207], v[104:107]
	v_mfma_f32_16x16x32_bf16 v[96:99], v[92:95], v[204:207], v[96:99]
	v_mfma_f32_16x16x32_bf16 v[168:171], v[88:91], v[120:123], v[168:171]
	v_mfma_f32_16x16x32_bf16 v[116:119], v[100:103], v[120:123], v[116:119]
	v_mfma_f32_16x16x32_bf16 v[120:123], v[84:87], v[140:143], v[152:155]
	v_mfma_f32_16x16x32_bf16 v[140:143], v[92:95], v[140:143], v[148:151]
	v_mfma_f32_16x16x32_bf16 v[128:131], v[88:91], v[200:203], v[128:131]
	v_mfma_f32_16x16x32_bf16 v[124:127], v[100:103], v[200:203], v[124:127]
	v_mfma_f32_16x16x32_bf16 v[104:107], v[88:91], v[208:211], v[104:107]
	v_mfma_f32_16x16x32_bf16 v[96:99], v[100:103], v[208:211], v[96:99]
	v_mfma_f32_16x16x32_bf16 v[120:123], v[88:91], v[144:147], v[120:123]
	v_mfma_f32_16x16x32_bf16 v[140:143], v[100:103], v[144:147], v[140:143]
	s_barrier
	s_add_i32 s54, s54, s27
	v_lshl_add_u64 v[234:235], s[52:53], 0, v[190:191]
	s_mov_b32 m0, s54
	ds_read_b128 v[144:147], v233 offset:16384
	ds_read_b128 v[148:151], v233 offset:17408
	ds_read_b128 v[152:155], v233 offset:18432
	ds_read_b128 v[164:167], v233 offset:19456
	ds_read_b128 v[180:183], v233 offset:20480
	ds_read_b128 v[200:203], v233 offset:21504
	ds_read_b128 v[204:207], v233 offset:22528
	ds_read_b128 v[208:211], v233 offset:23552
	global_load_lds_dwordx4 v[234:235], off
	s_add_i32 m0, s54, 0x2000
	v_lshl_add_u64 v[236:237], s[52:53], 0, v[194:195]
	s_add_u32 s52, s52, s2
	s_addc_u32 s53, s53, 0
	s_add_i32 s47, s47, s27
	global_load_lds_dwordx4 v[236:237], off
	v_lshl_add_u64 v[238:239], s[52:53], 0, v[190:191]
	s_mov_b32 m0, s47
	v_lshl_add_u64 v[240:241], s[52:53], 0, v[194:195]
	global_load_lds_dwordx4 v[238:239], off
	s_add_i32 m0, s47, 0x2000
	v_lshl_add_u64 v[242:243], s[20:21], 0, v[188:189]
	global_load_lds_dwordx4 v[240:241], off
	s_mov_b32 m0, s33
	v_lshl_add_u64 v[244:245], s[20:21], 0, v[192:193]
	global_load_lds_dwordx4 v[242:243], off
	s_mov_b32 m0, s34
	s_nop 0
	global_load_lds_dwordx4 v[244:245], off
	s_waitcnt vmcnt(8)
	s_waitcnt lgkmcnt(0)
	s_barrier
; #define PG8_STAGE(bufoff, gbase, voff) do { _Pragma("unroll") for (int _i = 0; _i < 2; ++_i) \
;         __builtin_amdgcn_global_load_lds((const unsigned*)((const char*)(gbase) + (voff)[_i]), (PG8_LAS unsigned*)(lds + (bufoff) + ldsw + _i * 8192), 16, 0, 0); } while (0)
; #define PG8_LDA(dst, b, h) do { _Pragma("unroll") for (int m = 0; m < 4; ++m) _Pragma("unroll") for (int k = 0; k < 2; ++k) dst[m][k] = *(const PG8_LAS bf16x8*)(lds + PG8_SA(b, h) + aoff + m * 2048 + k * 1024); } while (0)
; #define PG8_LDB(dst, b, h) do { _Pragma("unroll") for (int n = 0; n < 2; ++n) _Pragma("unroll") for (int k = 0; k < 2; ++k) dst[n][k] = *(const PG8_LAS bf16x8*)(lds + PG8_SB(b, h) + boff + n * 2048 + k * 1024); } while (0)
; #define PG8_MMA(ai, bj, At, Bt) do { __builtin_amdgcn_s_setprio(1); _Pragma("unroll") for (int m = 0; m < 4; ++m) _Pragma("unroll") for (int n = 0; n < 2; ++n) _Pragma("unroll") for (int k = 0; k < 2; ++k) \
;         acc[ai][bj][m][n] = __builtin_amdgcn_mfma_f32_16x16x32_bf16(Bt[n][k], At[m][k], acc[ai][bj][m][n], 0, 0, 0); __builtin_amdgcn_s_setprio(0); } while (0)
; #define PG8_WAIT_V(n) asm volatile("s_waitcnt vmcnt(" #n ")" ::: "memory")
; #define PG8_WAIT_L(n) asm volatile("s_waitcnt lgkmcnt(" #n ")" ::: "memory")
; #define PG8_BAR __builtin_amdgcn_s_barrier()
; #define PG8_SCHED __builtin_amdgcn_sched_barrier(0)
; template <class Epi, class Sched, bool ALIGN_EPI = false, bool SP2 = false>
; __device__ __forceinline__ void gemm_phase(PG8_LAS unsigned char* lds, const Gemm g, const Sched& S, const Epi& E) {
;     ...
;             PG8_WAIT_V(8); PG8_WAIT_L(0); PG8_BAR; PG8_MMA(1, 0, At, B0); PG8_MMA(1, 1, At, B1); PG8_BAR; PG8_SCHED;
;             PG8_LDB(B0, 1, 0); PG8_LDB(B1, 1, 1); PG8_SCHED; PG8_LDA(At, 1, 0); PG8_STAGE(PG8_SA(0, 1), a2 + hstep, voffA);
;             PG8_WAIT_V(8); PG8_WAIT_L(0); PG8_BAR; PG8_MMA(0, 0, At, B0); PG8_MMA(0, 1, At, B1); PG8_BAR; PG8_SCHED;
	v_mfma_f32_16x16x32_bf16 v[66:69], v[56:59], v[144:147], v[68:71]
	v_mfma_f32_16x16x32_bf16 v[60:63], v[76:79], v[144:147], v[60:63]
	v_mfma_f32_16x16x32_bf16 v[44:47], v[56:59], v[152:155], v[44:47]
	v_mfma_f32_16x16x32_bf16 v[40:43], v[76:79], v[152:155], v[40:43]
	v_mfma_f32_16x16x32_bf16 v[28:31], v[56:59], v[180:183], v[28:31]
	v_mfma_f32_16x16x32_bf16 v[24:27], v[76:79], v[180:183], v[24:27]
	v_mfma_f32_16x16x32_bf16 v[12:15], v[56:59], v[204:207], v[12:15]
	v_mfma_f32_16x16x32_bf16 v[8:11], v[76:79], v[204:207], v[8:11]
	v_mfma_f32_16x16x32_bf16 v[66:69], v[72:75], v[148:151], v[66:69]
	v_mfma_f32_16x16x32_bf16 v[60:63], v[80:83], v[148:151], v[60:63]
	v_mfma_f32_16x16x32_bf16 v[44:47], v[72:75], v[164:167], v[44:47]
	v_mfma_f32_16x16x32_bf16 v[40:43], v[80:83], v[164:167], v[40:43]
	v_mfma_f32_16x16x32_bf16 v[28:31], v[72:75], v[200:203], v[28:31]
	v_mfma_f32_16x16x32_bf16 v[24:27], v[80:83], v[200:203], v[24:27]
	v_mfma_f32_16x16x32_bf16 v[12:15], v[72:75], v[208:211], v[12:15]
	v_mfma_f32_16x16x32_bf16 v[8:11], v[80:83], v[208:211], v[8:11]
	v_mfma_f32_16x16x32_bf16 v[52:55], v[84:87], v[144:147], v[52:55]
	v_mfma_f32_16x16x32_bf16 v[48:51], v[92:95], v[144:147], v[48:51]
	v_mfma_f32_16x16x32_bf16 v[36:39], v[84:87], v[152:155], v[36:39]
	v_mfma_f32_16x16x32_bf16 v[32:35], v[92:95], v[152:155], v[32:35]
	v_mfma_f32_16x16x32_bf16 v[20:23], v[84:87], v[180:183], v[20:23]
	v_mfma_f32_16x16x32_bf16 v[16:19], v[92:95], v[180:183], v[16:19]
	v_mfma_f32_16x16x32_bf16 v[4:7], v[84:87], v[204:207], v[4:7]
	v_mfma_f32_16x16x32_bf16 v[0:3], v[92:95], v[204:207], v[0:3]
	v_mfma_f32_16x16x32_bf16 v[52:55], v[88:91], v[148:151], v[52:55]
	v_mfma_f32_16x16x32_bf16 v[48:51], v[100:103], v[148:151], v[48:51]
	v_mfma_f32_16x16x32_bf16 v[36:39], v[88:91], v[164:167], v[36:39]
	v_mfma_f32_16x16x32_bf16 v[32:35], v[100:103], v[164:167], v[32:35]
	v_mfma_f32_16x16x32_bf16 v[20:23], v[88:91], v[200:203], v[20:23]
	v_mfma_f32_16x16x32_bf16 v[16:19], v[100:103], v[200:203], v[16:19]
	v_mfma_f32_16x16x32_bf16 v[4:7], v[88:91], v[208:211], v[4:7]
	v_mfma_f32_16x16x32_bf16 v[0:3], v[100:103], v[208:211], v[0:3]
	s_barrier
	s_add_i32 s47, 0, 0x18000
	v_add_u32_e32 v64, s47, v231
	s_add_i32 s52, 0, 0x1c000
	ds_read_b128 v[56:59], v64
	ds_read_b128 v[72:75], v64 offset:1024
	ds_read_b128 v[76:79], v64 offset:2048
	ds_read_b128 v[80:83], v64 offset:3072
	v_add_u32_e32 v64, s52, v231
	ds_read_b128 v[84:87], v64
	ds_read_b128 v[88:91], v64 offset:1024
	ds_read_b128 v[92:95], v64 offset:2048
	ds_read_b128 v[100:103], v64 offset:3072
	s_add_u32 s20, s20, s2
	s_addc_u32 s21, s21, 0
	s_mov_b32 m0, s35
	v_lshl_add_u64 v[70:71], s[20:21], 0, v[188:189]
	ds_read_b128 v[144:147], v233 offset:32768
	ds_read_b128 v[148:151], v233 offset:33792
	ds_read_b128 v[180:183], v233 offset:34816
	ds_read_b128 v[200:203], v233 offset:35840
	ds_read_b128 v[204:207], v233 offset:36864
	ds_read_b128 v[208:211], v233 offset:37888
	ds_read_b128 v[212:215], v233 offset:38912
	ds_read_b128 v[216:219], v233 offset:39936
	global_load_lds_dwordx4 v[70:71], off
	v_lshl_add_u64 v[70:71], s[20:21], 0, v[192:193]
	s_mov_b32 m0, s36
	s_nop 0
	global_load_lds_dwordx4 v[70:71], off
	s_waitcnt vmcnt(8)
	s_waitcnt lgkmcnt(0)
	s_barrier
	v_mfma_f32_16x16x32_bf16 v[152:155], v[56:59], v[144:147], v[176:179]
	v_mfma_f32_16x16x32_bf16 v[176:179], v[72:75], v[148:151], v[152:155]
	v_mfma_f32_16x16x32_bf16 v[152:155], v[76:79], v[144:147], v[172:175]
	v_mfma_f32_16x16x32_bf16 v[172:175], v[80:83], v[148:151], v[152:155]
	v_mfma_f32_16x16x32_bf16 v[152:155], v[56:59], v[180:183], v[160:163]
	v_mfma_f32_16x16x32_bf16 v[160:163], v[72:75], v[200:203], v[152:155]
	v_mfma_f32_16x16x32_bf16 v[152:155], v[76:79], v[180:183], v[156:159]
	v_mfma_f32_16x16x32_bf16 v[136:139], v[56:59], v[204:207], v[136:139]
	v_mfma_f32_16x16x32_bf16 v[132:135], v[76:79], v[204:207], v[132:135]
	v_mfma_f32_16x16x32_bf16 v[112:115], v[56:59], v[212:215], v[112:115]
	v_mfma_f32_16x16x32_bf16 v[108:111], v[76:79], v[212:215], v[108:111]
	v_mfma_f32_16x16x32_bf16 v[156:159], v[80:83], v[200:203], v[152:155]
	v_mfma_f32_16x16x32_bf16 v[136:139], v[72:75], v[208:211], v[136:139]
	v_mfma_f32_16x16x32_bf16 v[132:135], v[80:83], v[208:211], v[132:135]
	v_mfma_f32_16x16x32_bf16 v[112:115], v[72:75], v[216:219], v[112:115]
	v_mfma_f32_16x16x32_bf16 v[108:111], v[80:83], v[216:219], v[108:111]
	v_mfma_f32_16x16x32_bf16 v[116:119], v[92:95], v[144:147], v[116:119]
	v_mfma_f32_16x16x32_bf16 v[152:155], v[84:87], v[144:147], v[168:171]
	v_mfma_f32_16x16x32_bf16 v[164:167], v[100:103], v[148:151], v[116:119]
	v_mfma_f32_16x16x32_bf16 v[116:119], v[84:87], v[180:183], v[120:123]
	v_mfma_f32_16x16x32_bf16 v[168:171], v[88:91], v[148:151], v[152:155]
	v_mfma_f32_16x16x32_bf16 v[152:155], v[88:91], v[200:203], v[116:119]
	v_mfma_f32_16x16x32_bf16 v[116:119], v[92:95], v[180:183], v[140:143]
	v_mfma_f32_16x16x32_bf16 v[148:151], v[100:103], v[200:203], v[116:119]
	v_mfma_f32_16x16x32_bf16 v[116:119], v[84:87], v[204:207], v[128:131]
	v_mfma_f32_16x16x32_bf16 v[128:131], v[88:91], v[208:211], v[116:119]
	v_mfma_f32_16x16x32_bf16 v[116:119], v[92:95], v[204:207], v[124:127]
	v_mfma_f32_16x16x32_bf16 v[104:107], v[84:87], v[212:215], v[104:107]
	v_mfma_f32_16x16x32_bf16 v[96:99], v[92:95], v[212:215], v[96:99]
	v_mfma_f32_16x16x32_bf16 v[124:127], v[100:103], v[208:211], v[116:119]
	v_mfma_f32_16x16x32_bf16 v[104:107], v[88:91], v[216:219], v[104:107]
	v_mfma_f32_16x16x32_bf16 v[96:99], v[100:103], v[216:219], v[96:99]
	s_barrier
; #define PG8_STAGE(bufoff, gbase, voff) do { _Pragma("unroll") for (int _i = 0; _i < 2; ++_i) \
;         __builtin_amdgcn_global_load_lds((const unsigned*)((const char*)(gbase) + (voff)[_i]), (PG8_LAS unsigned*)(lds + (bufoff) + ldsw + _i * 8192), 16, 0, 0); } while (0)
; #define PG8_LDA(dst, b, h) do { _Pragma("unroll") for (int m = 0; m < 4; ++m) _Pragma("unroll") for (int k = 0; k < 2; ++k) dst[m][k] = *(const PG8_LAS bf16x8*)(lds + PG8_SA(b, h) + aoff + m * 2048 + k * 1024); } while (0)
; #define PG8_MMA(ai, bj, At, Bt) do { __builtin_amdgcn_s_setprio(1); _Pragma("unroll") for (int m = 0; m < 4; ++m) _Pragma("unroll") for (int n = 0; n < 2; ++n) _Pragma("unroll") for (int k = 0; k < 2; ++k) \
;         acc[ai][bj][m][n] = __builtin_amdgcn_mfma_f32_16x16x32_bf16(Bt[n][k], At[m][k], acc[ai][bj][m][n], 0, 0, 0); __builtin_amdgcn_s_setprio(0); } while (0)
; #define PG8_WAIT_V(n) asm volatile("s_waitcnt vmcnt(" #n ")" ::: "memory")
; #define PG8_WAIT_L(n) asm volatile("s_waitcnt lgkmcnt(" #n ")" ::: "memory")
; #define PG8_BAR __builtin_amdgcn_s_barrier()
; #define PG8_SCHED __builtin_amdgcn_sched_barrier(0)
; template <class Epi, class Sched, bool ALIGN_EPI = false, bool SP2 = false>
; __device__ __forceinline__ void gemm_phase(PG8_LAS unsigned char* lds, const Gemm g, const Sched& S, const Epi& E) {
;     ...
;             PG8_LDA(At, 1, 1); PG8_STAGE(PG8_SB(1, 0), b3, voffB); PG8_STAGE(PG8_SB(1, 1), b3 + hstep, voffB); PG8_STAGE(PG8_SA(1, 0), a3, voffA);
;             PG8_WAIT_V(8); PG8_WAIT_L(0); PG8_BAR; PG8_MMA(1, 0, At, B0); PG8_MMA(1, 1, At, B1); PG8_BAR; PG8_SCHED;
	s_add_i32 s20, s47, s27
	v_lshl_add_u64 v[70:71], v[234:235], 0, s[56:57]
	s_mov_b32 m0, s20
	ds_read_b128 v[116:119], v233 offset:49152
	ds_read_b128 v[120:123], v233 offset:50176
	ds_read_b128 v[140:143], v233 offset:51200
	ds_read_b128 v[144:147], v233 offset:52224
	ds_read_b128 v[180:183], v233 offset:53248
	ds_read_b128 v[200:203], v233 offset:54272
	ds_read_b128 v[204:207], v233 offset:55296
	ds_read_b128 v[208:211], v233 offset:56320
	global_load_lds_dwordx4 v[70:71], off
	v_lshl_add_u64 v[70:71], v[236:237], 0, s[56:57]
	s_add_i32 m0, s20, 0x2000
	s_add_i32 s20, s52, s27
	global_load_lds_dwordx4 v[70:71], off
	v_lshl_add_u64 v[70:71], v[238:239], 0, s[56:57]
	s_mov_b32 m0, s20
	s_nop 0
	global_load_lds_dwordx4 v[70:71], off
	v_lshl_add_u64 v[70:71], v[240:241], 0, s[56:57]
	s_add_i32 m0, s20, 0x2000
	s_nop 0
	global_load_lds_dwordx4 v[70:71], off
	v_lshl_add_u64 v[70:71], v[242:243], 0, s[56:57]
	s_mov_b32 m0, s39
	s_nop 0
	global_load_lds_dwordx4 v[70:71], off
	v_lshl_add_u64 v[70:71], v[244:245], 0, s[56:57]
	s_mov_b32 m0, s40
	s_nop 0
	global_load_lds_dwordx4 v[70:71], off
	s_waitcnt vmcnt(8)
	s_waitcnt lgkmcnt(0)
	s_barrier
	v_mfma_f32_16x16x32_bf16 v[66:69], v[56:59], v[116:119], v[66:69]
	v_mfma_f32_16x16x32_bf16 v[60:63], v[76:79], v[116:119], v[60:63]
	v_mfma_f32_16x16x32_bf16 v[44:47], v[56:59], v[140:143], v[44:47]
	v_mfma_f32_16x16x32_bf16 v[40:43], v[76:79], v[140:143], v[40:43]
	v_mfma_f32_16x16x32_bf16 v[28:31], v[56:59], v[180:183], v[28:31]
	v_mfma_f32_16x16x32_bf16 v[24:27], v[76:79], v[180:183], v[24:27]
	v_mfma_f32_16x16x32_bf16 v[12:15], v[56:59], v[204:207], v[12:15]
	v_mfma_f32_16x16x32_bf16 v[8:11], v[76:79], v[204:207], v[8:11]
	v_mfma_f32_16x16x32_bf16 v[68:71], v[72:75], v[120:123], v[66:69]
	v_mfma_f32_16x16x32_bf16 v[60:63], v[80:83], v[120:123], v[60:63]
	v_mfma_f32_16x16x32_bf16 v[44:47], v[72:75], v[144:147], v[44:47]
	v_mfma_f32_16x16x32_bf16 v[40:43], v[80:83], v[144:147], v[40:43]
	v_mfma_f32_16x16x32_bf16 v[28:31], v[72:75], v[200:203], v[28:31]
	v_mfma_f32_16x16x32_bf16 v[24:27], v[80:83], v[200:203], v[24:27]
	v_mfma_f32_16x16x32_bf16 v[12:15], v[72:75], v[208:211], v[12:15]
	v_mfma_f32_16x16x32_bf16 v[8:11], v[80:83], v[208:211], v[8:11]
	v_mfma_f32_16x16x32_bf16 v[52:55], v[84:87], v[116:119], v[52:55]
	v_mfma_f32_16x16x32_bf16 v[48:51], v[92:95], v[116:119], v[48:51]
	v_mfma_f32_16x16x32_bf16 v[36:39], v[84:87], v[140:143], v[36:39]
	v_mfma_f32_16x16x32_bf16 v[32:35], v[92:95], v[140:143], v[32:35]
	v_mfma_f32_16x16x32_bf16 v[20:23], v[84:87], v[180:183], v[20:23]
	v_mfma_f32_16x16x32_bf16 v[16:19], v[92:95], v[180:183], v[16:19]
	v_mfma_f32_16x16x32_bf16 v[4:7], v[84:87], v[204:207], v[4:7]
	v_mfma_f32_16x16x32_bf16 v[0:3], v[92:95], v[204:207], v[0:3]
	v_mfma_f32_16x16x32_bf16 v[52:55], v[88:91], v[120:123], v[52:55]
	v_mfma_f32_16x16x32_bf16 v[48:51], v[100:103], v[120:123], v[48:51]
	v_mfma_f32_16x16x32_bf16 v[36:39], v[88:91], v[144:147], v[36:39]
	v_mfma_f32_16x16x32_bf16 v[32:35], v[100:103], v[144:147], v[32:35]
	v_mfma_f32_16x16x32_bf16 v[20:23], v[88:91], v[200:203], v[20:23]
	v_mfma_f32_16x16x32_bf16 v[16:19], v[100:103], v[200:203], v[16:19]
	v_mfma_f32_16x16x32_bf16 v[4:7], v[88:91], v[208:211], v[4:7]
	v_mfma_f32_16x16x32_bf16 v[0:3], v[100:103], v[208:211], v[0:3]
	s_barrier
	s_add_u32 s18, s18, 0x100
	s_addc_u32 s19, s19, 0
	s_add_u32 s22, s22, 0x100
	s_addc_u32 s23, s23, 0
	s_cmp_ge_u32 s46, s38
	s_mov_b32 s20, s46
	s_cbranch_scc0 .LBB0_97
	s_and_b64 vcc, exec, s[12:13]
	s_cbranch_vccz .LBB0_100
	s_barrier

; #define PG8_STAGE(bufoff, gbase, voff) do { _Pragma("unroll") for (int _i = 0; _i < 2; ++_i) \
;         __builtin_amdgcn_global_load_lds((const unsigned*)((const char*)(gbase) + (voff)[_i]), (PG8_LAS unsigned*)(lds + (bufoff) + ldsw + _i * 8192), 16, 0, 0); } while (0)
; #define PG8_LDA(dst, b, h) do { _Pragma("unroll") for (int m = 0; m < 4; ++m) _Pragma("unroll") for (int k = 0; k < 2; ++k) dst[m][k] = *(const PG8_LAS bf16x8*)(lds + PG8_SA(b, h) + aoff + m * 2048 + k * 1024); } while (0)
; #define PG8_LDB(dst, b, h) do { _Pragma("unroll") for (int n = 0; n < 2; ++n) _Pragma("unroll") for (int k = 0; k < 2; ++k) dst[n][k] = *(const PG8_LAS bf16x8*)(lds + PG8_SB(b, h) + boff + n * 2048 + k * 1024); } while (0)
; #define PG8_MMA(ai, bj, At, Bt) do { __builtin_amdgcn_s_setprio(1); _Pragma("unroll") for (int m = 0; m < 4; ++m) _Pragma("unroll") for (int n = 0; n < 2; ++n) _Pragma("unroll") for (int k = 0; k < 2; ++k) \
;         acc[ai][bj][m][n] = __builtin_amdgcn_mfma_f32_16x16x32_bf16(Bt[n][k], At[m][k], acc[ai][bj][m][n], 0, 0, 0); __builtin_amdgcn_s_setprio(0); } while (0)
; #define PG8_WAIT_V(n) asm volatile("s_waitcnt vmcnt(" #n ")" ::: "memory")
; #define PG8_WAIT_L(n) asm volatile("s_waitcnt lgkmcnt(" #n ")" ::: "memory")
; template <class Epi, class Sched, bool ALIGN_EPI = false, bool SP2 = false>
; __device__ __forceinline__ void gemm_phase(PG8_LAS unsigned char* lds, const Gemm g, const Sched& S, const Epi& E) {
;     ...
;             const bool last = (t == nt - 2);
;             const char* a1 = cA + (size_t)(t + 1) * kstep;
;             const char* a2 = last ? nA : cA + (size_t)(t + 2) * kstep; const char* b2 = last ? nB : cB + (size_t)(t + 2) * kstep;
;             const char* a3 = a2 + kstep; const char* b3 = b2 + kstep;
;             if (last && has_next) S.a_ready(nxt);
;             if constexpr (SP2) {
;             PG8_LDB(B0, 0, 0); PG8_LDB(B1, 0, 1); PG8_SCHED; PG8_LDA(At, 0, 0); PG8_STAGE(PG8_SA(1, 1), a1 + hstep, voffA);
;             PG8_WAIT_V(8); PG8_WAIT_L(0); PG8_BAR; PG8_MMA(0, 0, At, B0); PG8_MMA(0, 1, At, B1); PG8_BAR; PG8_SCHED;
;             PG8_LDA(At, 0, 1); PG8_STAGE(PG8_SB(0, 0), b2, voffB); PG8_STAGE(PG8_SB(0, 1), b2 + hstep, voffB); PG8_STAGE(PG8_SA(0, 0), a2, voffA);
;             PG8_WAIT_V(8); PG8_WAIT_L(0); PG8_BAR; PG8_MMA(1, 0, At, B0); PG8_MMA(1, 1, At, B1); PG8_BAR; PG8_SCHED;
.LBB0_252:
	s_add_u32 s18, s16, 0xfffc0080
	s_addc_u32 s19, s17, -1
	s_add_i32 s47, 0, 0x10000
	s_cmp_eq_u32 s46, 12
	s_cselect_b32 s21, s9, s19
	s_cselect_b32 s20, s40, s18
	v_add_u32_e32 v64, s47, v152
	s_cselect_b32 s19, s7, s45
	s_cselect_b32 s18, s41, s44
	s_add_i32 s50, 0, 0x14000
	ds_read_b128 v[142:145], v64
	ds_read_b128 v[158:161], v64 offset:1024
	ds_read_b128 v[162:165], v64 offset:2048
	ds_read_b128 v[166:169], v64 offset:3072
	v_add_u32_e32 v64, s50, v152
	ds_read_b128 v[170:173], v64
	ds_read_b128 v[174:177], v64 offset:1024
	ds_read_b128 v[178:181], v64 offset:2048
	ds_read_b128 v[188:191], v64 offset:3072
	v_lshl_add_u64 v[146:147], s[16:17], 0, v[138:139]
	s_add_i32 m0, s28, 0xc000
	ds_read_b128 v[192:195], v156
	ds_read_b128 v[196:199], v156 offset:1024
	ds_read_b128 v[200:203], v156 offset:2048
	ds_read_b128 v[204:207], v156 offset:3072
	ds_read_b128 v[208:211], v156 offset:4096
	ds_read_b128 v[212:215], v156 offset:5120
	ds_read_b128 v[216:219], v156 offset:6144
	ds_read_b128 v[230:233], v156 offset:7168
	global_load_lds_dwordx4 v[146:147], off
	v_lshl_add_u64 v[146:147], s[16:17], 0, v[140:141]
	s_add_i32 m0, s28, 0xe000
	s_nop 0
	global_load_lds_dwordx4 v[146:147], off
	s_waitcnt vmcnt(8)
	s_waitcnt lgkmcnt(0)
	s_barrier
	v_mfma_f32_16x16x32_bf16 v[126:129], v[142:145], v[192:195], v[126:129]
	v_mfma_f32_16x16x32_bf16 v[122:125], v[162:165], v[192:195], v[122:125]
	v_mfma_f32_16x16x32_bf16 v[114:117], v[142:145], v[200:203], v[114:117]
	v_mfma_f32_16x16x32_bf16 v[106:109], v[162:165], v[200:203], v[106:109]
	v_mfma_f32_16x16x32_bf16 v[102:105], v[142:145], v[208:211], v[102:105]
	v_mfma_f32_16x16x32_bf16 v[94:97], v[162:165], v[208:211], v[94:97]
	v_mfma_f32_16x16x32_bf16 v[82:85], v[142:145], v[216:219], v[82:85]
	v_mfma_f32_16x16x32_bf16 v[74:77], v[162:165], v[216:219], v[74:77]
	v_mfma_f32_16x16x32_bf16 v[126:129], v[158:161], v[196:199], v[126:129]
	v_mfma_f32_16x16x32_bf16 v[122:125], v[166:169], v[196:199], v[122:125]
	v_mfma_f32_16x16x32_bf16 v[114:117], v[158:161], v[204:207], v[114:117]
	v_mfma_f32_16x16x32_bf16 v[106:109], v[166:169], v[204:207], v[106:109]
	v_mfma_f32_16x16x32_bf16 v[102:105], v[158:161], v[212:215], v[102:105]
	v_mfma_f32_16x16x32_bf16 v[94:97], v[166:169], v[212:215], v[94:97]
	v_mfma_f32_16x16x32_bf16 v[82:85], v[158:161], v[230:233], v[82:85]
	v_mfma_f32_16x16x32_bf16 v[74:77], v[166:169], v[230:233], v[74:77]
	v_mfma_f32_16x16x32_bf16 v[118:121], v[170:173], v[192:195], v[118:121]
	v_mfma_f32_16x16x32_bf16 v[110:113], v[178:181], v[192:195], v[110:113]
	v_mfma_f32_16x16x32_bf16 v[98:101], v[170:173], v[200:203], v[98:101]
	v_mfma_f32_16x16x32_bf16 v[90:93], v[178:181], v[200:203], v[90:93]
	v_mfma_f32_16x16x32_bf16 v[86:89], v[170:173], v[208:211], v[86:89]
	v_mfma_f32_16x16x32_bf16 v[78:81], v[178:181], v[208:211], v[78:81]
	v_mfma_f32_16x16x32_bf16 v[70:73], v[170:173], v[216:219], v[70:73]
	v_mfma_f32_16x16x32_bf16 v[66:69], v[178:181], v[216:219], v[66:69]
	v_mfma_f32_16x16x32_bf16 v[118:121], v[174:177], v[196:199], v[118:121]
	v_mfma_f32_16x16x32_bf16 v[110:113], v[188:191], v[196:199], v[110:113]
	v_mfma_f32_16x16x32_bf16 v[98:101], v[174:177], v[204:207], v[98:101]
	v_mfma_f32_16x16x32_bf16 v[90:93], v[188:191], v[204:207], v[90:93]
	v_mfma_f32_16x16x32_bf16 v[86:89], v[174:177], v[212:215], v[86:89]
	v_mfma_f32_16x16x32_bf16 v[78:81], v[188:191], v[212:215], v[78:81]
	v_mfma_f32_16x16x32_bf16 v[70:73], v[174:177], v[230:233], v[70:73]
	v_mfma_f32_16x16x32_bf16 v[66:69], v[188:191], v[230:233], v[66:69]
	s_barrier
	s_add_i32 s47, s47, s27
	v_lshl_add_u64 v[146:147], s[18:19], 0, v[134:135]
	s_mov_b32 m0, s47
	ds_read_b128 v[192:195], v156 offset:16384
	ds_read_b128 v[196:199], v156 offset:17408
	ds_read_b128 v[200:203], v156 offset:18432
	ds_read_b128 v[204:207], v156 offset:19456
	ds_read_b128 v[208:211], v156 offset:20480
	ds_read_b128 v[212:215], v156 offset:21504
	ds_read_b128 v[216:219], v156 offset:22528
	ds_read_b128 v[230:233], v156 offset:23552
	global_load_lds_dwordx4 v[146:147], off
	s_add_i32 m0, s47, 0x2000
	s_add_u32 s48, s18, 0x40000
	v_lshl_add_u64 v[150:151], s[18:19], 0, v[130:131]
	s_addc_u32 s49, s19, 0
	s_add_i32 s47, s50, s27
	global_load_lds_dwordx4 v[150:151], off
	v_lshl_add_u64 v[182:183], s[48:49], 0, v[134:135]
	s_mov_b32 m0, s47
	v_lshl_add_u64 v[234:235], s[20:21], 0, v[132:133]
	global_load_lds_dwordx4 v[182:183], off
	v_lshl_add_u64 v[182:183], s[48:49], 0, v[130:131]
	s_add_i32 m0, s47, 0x2000
	s_nop 0
	global_load_lds_dwordx4 v[182:183], off
	v_lshl_add_u64 v[182:183], s[20:21], 0, v[136:137]
	s_mov_b32 m0, s28
	s_nop 0
	global_load_lds_dwordx4 v[182:183], off
	s_mov_b32 m0, s29
	s_nop 0
	global_load_lds_dwordx4 v[234:235], off
	s_waitcnt vmcnt(8)
	s_waitcnt lgkmcnt(0)
	s_barrier
; #define PG8_STAGE(bufoff, gbase, voff) do { _Pragma("unroll") for (int _i = 0; _i < 2; ++_i) \
;         __builtin_amdgcn_global_load_lds((const unsigned*)((const char*)(gbase) + (voff)[_i]), (PG8_LAS unsigned*)(lds + (bufoff) + ldsw + _i * 8192), 16, 0, 0); } while (0)
; #define PG8_LDA(dst, b, h) do { _Pragma("unroll") for (int m = 0; m < 4; ++m) _Pragma("unroll") for (int k = 0; k < 2; ++k) dst[m][k] = *(const PG8_LAS bf16x8*)(lds + PG8_SA(b, h) + aoff + m * 2048 + k * 1024); } while (0)
; #define PG8_LDB(dst, b, h) do { _Pragma("unroll") for (int n = 0; n < 2; ++n) _Pragma("unroll") for (int k = 0; k < 2; ++k) dst[n][k] = *(const PG8_LAS bf16x8*)(lds + PG8_SB(b, h) + boff + n * 2048 + k * 1024); } while (0)
; #define PG8_MMA(ai, bj, At, Bt) do { __builtin_amdgcn_s_setprio(1); _Pragma("unroll") for (int m = 0; m < 4; ++m) _Pragma("unroll") for (int n = 0; n < 2; ++n) _Pragma("unroll") for (int k = 0; k < 2; ++k) \
;         acc[ai][bj][m][n] = __builtin_amdgcn_mfma_f32_16x16x32_bf16(Bt[n][k], At[m][k], acc[ai][bj][m][n], 0, 0, 0); __builtin_amdgcn_s_setprio(0); } while (0)
; #define PG8_WAIT_V(n) asm volatile("s_waitcnt vmcnt(" #n ")" ::: "memory")
; #define PG8_WAIT_L(n) asm volatile("s_waitcnt lgkmcnt(" #n ")" ::: "memory")
; #define PG8_BAR __builtin_amdgcn_s_barrier()
; #define PG8_SCHED __builtin_amdgcn_sched_barrier(0)
; template <class Epi, class Sched, bool ALIGN_EPI = false, bool SP2 = false>
; __device__ __forceinline__ void gemm_phase(PG8_LAS unsigned char* lds, const Gemm g, const Sched& S, const Epi& E) {
;     ...
;             PG8_WAIT_V(8); PG8_WAIT_L(0); PG8_BAR; PG8_MMA(1, 0, At, B0); PG8_MMA(1, 1, At, B1); PG8_BAR; PG8_SCHED;
;             PG8_LDB(B0, 1, 0); PG8_LDB(B1, 1, 1); PG8_SCHED; PG8_LDA(At, 1, 0); PG8_STAGE(PG8_SA(0, 1), a2 + hstep, voffA);
;             PG8_WAIT_V(8); PG8_WAIT_L(0); PG8_BAR; PG8_MMA(0, 0, At, B0); PG8_MMA(0, 1, At, B1); PG8_BAR; PG8_SCHED;
	v_mfma_f32_16x16x32_bf16 v[60:63], v[142:145], v[192:195], v[60:63]
	v_mfma_f32_16x16x32_bf16 v[56:59], v[162:165], v[192:195], v[56:59]
	v_mfma_f32_16x16x32_bf16 v[48:51], v[142:145], v[200:203], v[48:51]
	v_mfma_f32_16x16x32_bf16 v[40:43], v[162:165], v[200:203], v[40:43]
	v_mfma_f32_16x16x32_bf16 v[36:39], v[142:145], v[208:211], v[36:39]
	v_mfma_f32_16x16x32_bf16 v[28:31], v[162:165], v[208:211], v[28:31]
	v_mfma_f32_16x16x32_bf16 v[20:23], v[142:145], v[216:219], v[20:23]
	v_mfma_f32_16x16x32_bf16 v[12:15], v[162:165], v[216:219], v[12:15]
	v_mfma_f32_16x16x32_bf16 v[60:63], v[158:161], v[196:199], v[60:63]
	v_mfma_f32_16x16x32_bf16 v[56:59], v[166:169], v[196:199], v[56:59]
	v_mfma_f32_16x16x32_bf16 v[48:51], v[158:161], v[204:207], v[48:51]
	v_mfma_f32_16x16x32_bf16 v[40:43], v[166:169], v[204:207], v[40:43]
	v_mfma_f32_16x16x32_bf16 v[36:39], v[158:161], v[212:215], v[36:39]
	v_mfma_f32_16x16x32_bf16 v[28:31], v[166:169], v[212:215], v[28:31]
	v_mfma_f32_16x16x32_bf16 v[20:23], v[158:161], v[230:233], v[20:23]
	v_mfma_f32_16x16x32_bf16 v[12:15], v[166:169], v[230:233], v[12:15]
	v_mfma_f32_16x16x32_bf16 v[52:55], v[170:173], v[192:195], v[52:55]
	v_mfma_f32_16x16x32_bf16 v[44:47], v[178:181], v[192:195], v[44:47]
	v_mfma_f32_16x16x32_bf16 v[32:35], v[170:173], v[200:203], v[32:35]
	v_mfma_f32_16x16x32_bf16 v[24:27], v[178:181], v[200:203], v[24:27]
	v_mfma_f32_16x16x32_bf16 v[16:19], v[170:173], v[208:211], v[16:19]
	v_mfma_f32_16x16x32_bf16 v[8:11], v[178:181], v[208:211], v[8:11]
	v_mfma_f32_16x16x32_bf16 v[4:7], v[170:173], v[216:219], v[4:7]
	v_mfma_f32_16x16x32_bf16 v[0:3], v[178:181], v[216:219], v[0:3]
	v_mfma_f32_16x16x32_bf16 v[52:55], v[174:177], v[196:199], v[52:55]
	v_mfma_f32_16x16x32_bf16 v[44:47], v[188:191], v[196:199], v[44:47]
	v_mfma_f32_16x16x32_bf16 v[32:35], v[174:177], v[204:207], v[32:35]
	v_mfma_f32_16x16x32_bf16 v[24:27], v[188:191], v[204:207], v[24:27]
	v_mfma_f32_16x16x32_bf16 v[16:19], v[174:177], v[212:215], v[16:19]
	v_mfma_f32_16x16x32_bf16 v[8:11], v[188:191], v[212:215], v[8:11]
	v_mfma_f32_16x16x32_bf16 v[4:7], v[174:177], v[230:233], v[4:7]
	v_mfma_f32_16x16x32_bf16 v[0:3], v[188:191], v[230:233], v[0:3]
	s_barrier
	s_add_i32 s47, 0, 0x18000
	v_add_u32_e32 v64, s47, v152
	s_add_i32 s48, 0, 0x1c000
	ds_read_b128 v[142:145], v64
	ds_read_b128 v[158:161], v64 offset:1024
	ds_read_b128 v[162:165], v64 offset:2048
	ds_read_b128 v[166:169], v64 offset:3072
	v_add_u32_e32 v64, s48, v152
	ds_read_b128 v[170:173], v64
	ds_read_b128 v[174:177], v64 offset:1024
	ds_read_b128 v[178:181], v64 offset:2048
	ds_read_b128 v[188:191], v64 offset:3072
	s_add_u32 s20, s20, 0x40000
	s_addc_u32 s21, s21, 0
	s_mov_b32 m0, s33
	v_lshl_add_u64 v[236:237], s[20:21], 0, v[136:137]
	ds_read_b128 v[192:195], v156 offset:32768
	ds_read_b128 v[196:199], v156 offset:33792
	ds_read_b128 v[200:203], v156 offset:34816
	ds_read_b128 v[204:207], v156 offset:35840
	ds_read_b128 v[208:211], v156 offset:36864
	ds_read_b128 v[212:215], v156 offset:37888
	ds_read_b128 v[216:219], v156 offset:38912
	ds_read_b128 v[230:233], v156 offset:39936
	global_load_lds_dwordx4 v[236:237], off
	v_lshl_add_u64 v[236:237], s[20:21], 0, v[132:133]
	s_mov_b32 m0, s34
	s_nop 0
	global_load_lds_dwordx4 v[236:237], off
	s_waitcnt vmcnt(8)
	s_waitcnt lgkmcnt(0)
	s_barrier
	v_mfma_f32_16x16x32_bf16 v[126:129], v[142:145], v[192:195], v[126:129]
	v_mfma_f32_16x16x32_bf16 v[122:125], v[162:165], v[192:195], v[122:125]
	v_mfma_f32_16x16x32_bf16 v[114:117], v[142:145], v[200:203], v[114:117]
	v_mfma_f32_16x16x32_bf16 v[106:109], v[162:165], v[200:203], v[106:109]
	v_mfma_f32_16x16x32_bf16 v[102:105], v[142:145], v[208:211], v[102:105]
	v_mfma_f32_16x16x32_bf16 v[94:97], v[162:165], v[208:211], v[94:97]
	v_mfma_f32_16x16x32_bf16 v[82:85], v[142:145], v[216:219], v[82:85]
	v_mfma_f32_16x16x32_bf16 v[74:77], v[162:165], v[216:219], v[74:77]
	v_mfma_f32_16x16x32_bf16 v[126:129], v[158:161], v[196:199], v[126:129]
	v_mfma_f32_16x16x32_bf16 v[122:125], v[166:169], v[196:199], v[122:125]
	v_mfma_f32_16x16x32_bf16 v[114:117], v[158:161], v[204:207], v[114:117]
	v_mfma_f32_16x16x32_bf16 v[106:109], v[166:169], v[204:207], v[106:109]
	v_mfma_f32_16x16x32_bf16 v[102:105], v[158:161], v[212:215], v[102:105]
	v_mfma_f32_16x16x32_bf16 v[94:97], v[166:169], v[212:215], v[94:97]
	v_mfma_f32_16x16x32_bf16 v[82:85], v[158:161], v[230:233], v[82:85]
	v_mfma_f32_16x16x32_bf16 v[74:77], v[166:169], v[230:233], v[74:77]
	v_mfma_f32_16x16x32_bf16 v[118:121], v[170:173], v[192:195], v[118:121]
	v_mfma_f32_16x16x32_bf16 v[110:113], v[178:181], v[192:195], v[110:113]
	v_mfma_f32_16x16x32_bf16 v[98:101], v[170:173], v[200:203], v[98:101]
	v_mfma_f32_16x16x32_bf16 v[90:93], v[178:181], v[200:203], v[90:93]
	v_mfma_f32_16x16x32_bf16 v[86:89], v[170:173], v[208:211], v[86:89]
	v_mfma_f32_16x16x32_bf16 v[78:81], v[178:181], v[208:211], v[78:81]
	v_mfma_f32_16x16x32_bf16 v[70:73], v[170:173], v[216:219], v[70:73]
	v_mfma_f32_16x16x32_bf16 v[66:69], v[178:181], v[216:219], v[66:69]
	v_mfma_f32_16x16x32_bf16 v[118:121], v[174:177], v[196:199], v[118:121]
	v_mfma_f32_16x16x32_bf16 v[110:113], v[188:191], v[196:199], v[110:113]
	v_mfma_f32_16x16x32_bf16 v[98:101], v[174:177], v[204:207], v[98:101]
	v_mfma_f32_16x16x32_bf16 v[90:93], v[188:191], v[204:207], v[90:93]
	v_mfma_f32_16x16x32_bf16 v[86:89], v[174:177], v[212:215], v[86:89]
	v_mfma_f32_16x16x32_bf16 v[78:81], v[188:191], v[212:215], v[78:81]
	v_mfma_f32_16x16x32_bf16 v[70:73], v[174:177], v[230:233], v[70:73]
	v_mfma_f32_16x16x32_bf16 v[66:69], v[188:191], v[230:233], v[66:69]
	s_barrier
; #define PG8_STAGE(bufoff, gbase, voff) do { _Pragma("unroll") for (int _i = 0; _i < 2; ++_i) \
;         __builtin_amdgcn_global_load_lds((const unsigned*)((const char*)(gbase) + (voff)[_i]), (PG8_LAS unsigned*)(lds + (bufoff) + ldsw + _i * 8192), 16, 0, 0); } while (0)
; #define PG8_LDA(dst, b, h) do { _Pragma("unroll") for (int m = 0; m < 4; ++m) _Pragma("unroll") for (int k = 0; k < 2; ++k) dst[m][k] = *(const PG8_LAS bf16x8*)(lds + PG8_SA(b, h) + aoff + m * 2048 + k * 1024); } while (0)
; #define PG8_MMA(ai, bj, At, Bt) do { __builtin_amdgcn_s_setprio(1); _Pragma("unroll") for (int m = 0; m < 4; ++m) _Pragma("unroll") for (int n = 0; n < 2; ++n) _Pragma("unroll") for (int k = 0; k < 2; ++k) \
;         acc[ai][bj][m][n] = __builtin_amdgcn_mfma_f32_16x16x32_bf16(Bt[n][k], At[m][k], acc[ai][bj][m][n], 0, 0, 0); __builtin_amdgcn_s_setprio(0); } while (0)
; #define PG8_WAIT_V(n) asm volatile("s_waitcnt vmcnt(" #n ")" ::: "memory")
; #define PG8_WAIT_L(n) asm volatile("s_waitcnt lgkmcnt(" #n ")" ::: "memory")
; #define PG8_BAR __builtin_amdgcn_s_barrier()
; #define PG8_SCHED __builtin_amdgcn_sched_barrier(0)
; template <class Epi, class Sched, bool ALIGN_EPI = false, bool SP2 = false>
; __device__ __forceinline__ void gemm_phase(PG8_LAS unsigned char* lds, const Gemm g, const Sched& S, const Epi& E) {
;     ...
;             PG8_LDA(At, 1, 1); PG8_STAGE(PG8_SB(1, 0), b3, voffB); PG8_STAGE(PG8_SB(1, 1), b3 + hstep, voffB); PG8_STAGE(PG8_SA(1, 0), a3, voffA);
;             PG8_WAIT_V(8); PG8_WAIT_L(0); PG8_BAR; PG8_MMA(1, 0, At, B0); PG8_MMA(1, 1, At, B1); PG8_BAR; PG8_SCHED;
	s_add_i32 s20, s47, s27
	v_lshl_add_u64 v[146:147], v[146:147], 0, s[52:53]
	s_mov_b32 m0, s20
	ds_read_b128 v[192:195], v156 offset:49152
	ds_read_b128 v[196:199], v156 offset:50176
	ds_read_b128 v[200:203], v156 offset:51200
	ds_read_b128 v[204:207], v156 offset:52224
	ds_read_b128 v[208:211], v156 offset:53248
	ds_read_b128 v[212:215], v156 offset:54272
	ds_read_b128 v[216:219], v156 offset:55296
	ds_read_b128 v[230:233], v156 offset:56320
	global_load_lds_dwordx4 v[146:147], off
	s_add_i32 m0, s20, 0x2000
	s_add_u32 s18, s18, 0x40080
	v_lshl_add_u64 v[146:147], v[150:151], 0, s[52:53]
	s_addc_u32 s19, s19, 0
	s_add_i32 s20, s48, s27
	global_load_lds_dwordx4 v[146:147], off
	v_lshl_add_u64 v[146:147], s[18:19], 0, v[134:135]
	s_mov_b32 m0, s20
	s_nop 0
	global_load_lds_dwordx4 v[146:147], off
	v_lshl_add_u64 v[146:147], s[18:19], 0, v[130:131]
	s_add_i32 m0, s20, 0x2000
	s_nop 0
	global_load_lds_dwordx4 v[146:147], off
	v_lshl_add_u64 v[146:147], v[182:183], 0, s[52:53]
	s_mov_b32 m0, s35
	s_nop 0
	global_load_lds_dwordx4 v[146:147], off
	v_lshl_add_u64 v[146:147], v[234:235], 0, s[52:53]
	s_mov_b32 m0, s36
	s_nop 0
	global_load_lds_dwordx4 v[146:147], off
	s_waitcnt vmcnt(8)
	s_waitcnt lgkmcnt(0)
	s_barrier
	v_mfma_f32_16x16x32_bf16 v[60:63], v[142:145], v[192:195], v[60:63]
	v_mfma_f32_16x16x32_bf16 v[56:59], v[162:165], v[192:195], v[56:59]
	v_mfma_f32_16x16x32_bf16 v[48:51], v[142:145], v[200:203], v[48:51]
	v_mfma_f32_16x16x32_bf16 v[40:43], v[162:165], v[200:203], v[40:43]
	v_mfma_f32_16x16x32_bf16 v[36:39], v[142:145], v[208:211], v[36:39]
	v_mfma_f32_16x16x32_bf16 v[28:31], v[162:165], v[208:211], v[28:31]
	v_mfma_f32_16x16x32_bf16 v[20:23], v[142:145], v[216:219], v[20:23]
	v_mfma_f32_16x16x32_bf16 v[12:15], v[162:165], v[216:219], v[12:15]
	v_mfma_f32_16x16x32_bf16 v[60:63], v[158:161], v[196:199], v[60:63]
	v_mfma_f32_16x16x32_bf16 v[56:59], v[166:169], v[196:199], v[56:59]
	v_mfma_f32_16x16x32_bf16 v[48:51], v[158:161], v[204:207], v[48:51]
	v_mfma_f32_16x16x32_bf16 v[40:43], v[166:169], v[204:207], v[40:43]
	v_mfma_f32_16x16x32_bf16 v[36:39], v[158:161], v[212:215], v[36:39]
	v_mfma_f32_16x16x32_bf16 v[28:31], v[166:169], v[212:215], v[28:31]
	v_mfma_f32_16x16x32_bf16 v[20:23], v[158:161], v[230:233], v[20:23]
	v_mfma_f32_16x16x32_bf16 v[12:15], v[166:169], v[230:233], v[12:15]
	v_mfma_f32_16x16x32_bf16 v[52:55], v[170:173], v[192:195], v[52:55]
	v_mfma_f32_16x16x32_bf16 v[44:47], v[178:181], v[192:195], v[44:47]
	v_mfma_f32_16x16x32_bf16 v[32:35], v[170:173], v[200:203], v[32:35]
	v_mfma_f32_16x16x32_bf16 v[24:27], v[178:181], v[200:203], v[24:27]
	v_mfma_f32_16x16x32_bf16 v[16:19], v[170:173], v[208:211], v[16:19]
	v_mfma_f32_16x16x32_bf16 v[8:11], v[178:181], v[208:211], v[8:11]
	v_mfma_f32_16x16x32_bf16 v[4:7], v[170:173], v[216:219], v[4:7]
	v_mfma_f32_16x16x32_bf16 v[0:3], v[178:181], v[216:219], v[0:3]
	v_mfma_f32_16x16x32_bf16 v[52:55], v[174:177], v[196:199], v[52:55]
	v_mfma_f32_16x16x32_bf16 v[44:47], v[188:191], v[196:199], v[44:47]
	v_mfma_f32_16x16x32_bf16 v[32:35], v[174:177], v[204:207], v[32:35]
	v_mfma_f32_16x16x32_bf16 v[24:27], v[188:191], v[204:207], v[24:27]
	v_mfma_f32_16x16x32_bf16 v[16:19], v[174:177], v[212:215], v[16:19]
	v_mfma_f32_16x16x32_bf16 v[8:11], v[188:191], v[212:215], v[8:11]
	v_mfma_f32_16x16x32_bf16 v[4:7], v[174:177], v[230:233], v[4:7]
	v_mfma_f32_16x16x32_bf16 v[0:3], v[188:191], v[230:233], v[0:3]
	s_barrier
	s_add_i32 s46, s46, 2
	s_add_u32 s16, s16, 0x100
	s_addc_u32 s17, s17, 0
	s_add_u32 s44, s44, 0x100
	s_addc_u32 s45, s45, 0
	s_cmp_gt_u32 s46, 13
	s_cbranch_scc0 .LBB0_252
	s_and_b64 vcc, exec, s[4:5]
	s_cbranch_vccz .LBB0_255
	s_barrier

; #define PG8_STAGE(bufoff, gbase, voff) do { _Pragma("unroll") for (int _i = 0; _i < 2; ++_i) \
;         __builtin_amdgcn_global_load_lds((const unsigned*)((const char*)(gbase) + (voff)[_i]), (PG8_LAS unsigned*)(lds + (bufoff) + ldsw + _i * 8192), 16, 0, 0); } while (0)
; #define PG8_LDA(dst, b, h) do { _Pragma("unroll") for (int m = 0; m < 4; ++m) _Pragma("unroll") for (int k = 0; k < 2; ++k) dst[m][k] = *(const PG8_LAS bf16x8*)(lds + PG8_SA(b, h) + aoff + m * 2048 + k * 1024); } while (0)
; #define PG8_LDB(dst, b, h) do { _Pragma("unroll") for (int n = 0; n < 2; ++n) _Pragma("unroll") for (int k = 0; k < 2; ++k) dst[n][k] = *(const PG8_LAS bf16x8*)(lds + PG8_SB(b, h) + boff + n * 2048 + k * 1024); } while (0)
; #define PG8_MMA(ai, bj, At, Bt) do { __builtin_amdgcn_s_setprio(1); _Pragma("unroll") for (int m = 0; m < 4; ++m) _Pragma("unroll") for (int n = 0; n < 2; ++n) _Pragma("unroll") for (int k = 0; k < 2; ++k) \
;         acc[ai][bj][m][n] = __builtin_amdgcn_mfma_f32_16x16x32_bf16(Bt[n][k], At[m][k], acc[ai][bj][m][n], 0, 0, 0); __builtin_amdgcn_s_setprio(0); } while (0)
; #define PG8_WAIT_V(n) asm volatile("s_waitcnt vmcnt(" #n ")" ::: "memory")
; #define PG8_WAIT_L(n) asm volatile("s_waitcnt lgkmcnt(" #n ")" ::: "memory")
; template <class Epi, class Sched, bool ALIGN_EPI = false, bool SP2 = false>
; __device__ __forceinline__ void gemm_phase(PG8_LAS unsigned char* lds, const Gemm g, const Sched& S, const Epi& E) {
;     ...
;             const bool last = (t == nt - 2);
;             const char* a1 = cA + (size_t)(t + 1) * kstep;
;             const char* a2 = last ? nA : cA + (size_t)(t + 2) * kstep; const char* b2 = last ? nB : cB + (size_t)(t + 2) * kstep;
;             const char* a3 = a2 + kstep; const char* b3 = b2 + kstep;
;             if (last && has_next) S.a_ready(nxt);
;             if constexpr (SP2) {
;             PG8_LDB(B0, 0, 0); PG8_LDB(B1, 0, 1); PG8_SCHED; PG8_LDA(At, 0, 0); PG8_STAGE(PG8_SA(1, 1), a1 + hstep, voffA);
;             PG8_WAIT_V(8); PG8_WAIT_L(0); PG8_BAR; PG8_MMA(0, 0, At, B0); PG8_MMA(0, 1, At, B1); PG8_BAR; PG8_SCHED;
;             PG8_LDA(At, 0, 1); PG8_STAGE(PG8_SB(0, 0), b2, voffB); PG8_STAGE(PG8_SB(0, 1), b2 + hstep, voffB); PG8_STAGE(PG8_SA(0, 0), a2, voffA);
;             PG8_WAIT_V(8); PG8_WAIT_L(0); PG8_BAR; PG8_MMA(1, 0, At, B0); PG8_MMA(1, 1, At, B1); PG8_BAR; PG8_SCHED;
.LBB0_473:
	s_add_u32 s8, s6, 0xfffc0080
	s_addc_u32 s9, s7, -1
	s_add_i32 s33, 0, 0x10000
	s_cmp_eq_u32 s29, 12
	s_cselect_b32 s11, s5, s9
	s_cselect_b32 s10, s24, s8
	v_add_u32_e32 v64, s33, v161
	s_cselect_b32 s9, s25, s28
	s_cselect_b32 s8, s26, s27
	s_add_i32 s36, 0, 0x14000
	ds_read_b128 v[130:133], v64
	ds_read_b128 v[134:137], v64 offset:1024
	ds_read_b128 v[138:141], v64 offset:2048
	ds_read_b128 v[142:145], v64 offset:3072
	v_add_u32_e32 v64, s36, v161
	ds_read_b128 v[166:169], v64
	ds_read_b128 v[170:173], v64 offset:1024
	ds_read_b128 v[174:177], v64 offset:2048
	ds_read_b128 v[178:181], v64 offset:3072
	v_lshl_add_u64 v[158:159], s[6:7], 0, v[154:155]
	s_add_i32 m0, s16, 0xc000
	ds_read_b128 v[188:191], v164
	ds_read_b128 v[192:195], v164 offset:1024
	ds_read_b128 v[196:199], v164 offset:2048
	ds_read_b128 v[200:203], v164 offset:3072
	ds_read_b128 v[204:207], v164 offset:4096
	ds_read_b128 v[208:211], v164 offset:5120
	ds_read_b128 v[212:215], v164 offset:6144
	ds_read_b128 v[216:219], v164 offset:7168
	global_load_lds_dwordx4 v[158:159], off
	v_lshl_add_u64 v[158:159], s[6:7], 0, v[156:157]
	s_add_i32 m0, s16, 0xe000
	s_nop 0
	global_load_lds_dwordx4 v[158:159], off
	s_waitcnt vmcnt(8)
	s_waitcnt lgkmcnt(0)
	s_barrier
	v_mfma_f32_16x16x32_bf16 v[126:129], v[130:133], v[188:191], v[126:129]
	v_mfma_f32_16x16x32_bf16 v[122:125], v[138:141], v[188:191], v[122:125]
	v_mfma_f32_16x16x32_bf16 v[110:113], v[130:133], v[196:199], v[110:113]
	v_mfma_f32_16x16x32_bf16 v[106:109], v[138:141], v[196:199], v[106:109]
	v_mfma_f32_16x16x32_bf16 v[94:97], v[130:133], v[204:207], v[94:97]
	v_mfma_f32_16x16x32_bf16 v[90:93], v[138:141], v[204:207], v[90:93]
	v_mfma_f32_16x16x32_bf16 v[78:81], v[130:133], v[212:215], v[78:81]
	v_mfma_f32_16x16x32_bf16 v[74:77], v[138:141], v[212:215], v[74:77]
	v_mfma_f32_16x16x32_bf16 v[126:129], v[134:137], v[192:195], v[126:129]
	v_mfma_f32_16x16x32_bf16 v[122:125], v[142:145], v[192:195], v[122:125]
	v_mfma_f32_16x16x32_bf16 v[110:113], v[134:137], v[200:203], v[110:113]
	v_mfma_f32_16x16x32_bf16 v[106:109], v[142:145], v[200:203], v[106:109]
	v_mfma_f32_16x16x32_bf16 v[94:97], v[134:137], v[208:211], v[94:97]
	v_mfma_f32_16x16x32_bf16 v[90:93], v[142:145], v[208:211], v[90:93]
	v_mfma_f32_16x16x32_bf16 v[78:81], v[134:137], v[216:219], v[78:81]
	v_mfma_f32_16x16x32_bf16 v[74:77], v[142:145], v[216:219], v[74:77]
	v_mfma_f32_16x16x32_bf16 v[118:121], v[166:169], v[188:191], v[118:121]
	v_mfma_f32_16x16x32_bf16 v[114:117], v[174:177], v[188:191], v[114:117]
	v_mfma_f32_16x16x32_bf16 v[102:105], v[166:169], v[196:199], v[102:105]
	v_mfma_f32_16x16x32_bf16 v[98:101], v[174:177], v[196:199], v[98:101]
	v_mfma_f32_16x16x32_bf16 v[86:89], v[166:169], v[204:207], v[86:89]
	v_mfma_f32_16x16x32_bf16 v[82:85], v[174:177], v[204:207], v[82:85]
	v_mfma_f32_16x16x32_bf16 v[70:73], v[166:169], v[212:215], v[70:73]
	v_mfma_f32_16x16x32_bf16 v[66:69], v[174:177], v[212:215], v[66:69]
	v_mfma_f32_16x16x32_bf16 v[118:121], v[170:173], v[192:195], v[118:121]
	v_mfma_f32_16x16x32_bf16 v[114:117], v[178:181], v[192:195], v[114:117]
	v_mfma_f32_16x16x32_bf16 v[102:105], v[170:173], v[200:203], v[102:105]
	v_mfma_f32_16x16x32_bf16 v[98:101], v[178:181], v[200:203], v[98:101]
	v_mfma_f32_16x16x32_bf16 v[86:89], v[170:173], v[208:211], v[86:89]
	v_mfma_f32_16x16x32_bf16 v[82:85], v[178:181], v[208:211], v[82:85]
	v_mfma_f32_16x16x32_bf16 v[70:73], v[170:173], v[216:219], v[70:73]
	v_mfma_f32_16x16x32_bf16 v[66:69], v[178:181], v[216:219], v[66:69]
	s_barrier
	s_add_i32 s33, s33, s15
	v_lshl_add_u64 v[158:159], s[8:9], 0, v[148:149]
	s_mov_b32 m0, s33
	ds_read_b128 v[188:191], v164 offset:16384
	ds_read_b128 v[192:195], v164 offset:17408
	ds_read_b128 v[196:199], v164 offset:18432
	ds_read_b128 v[200:203], v164 offset:19456
	ds_read_b128 v[204:207], v164 offset:20480
	ds_read_b128 v[208:211], v164 offset:21504
	ds_read_b128 v[212:215], v164 offset:22528
	ds_read_b128 v[216:219], v164 offset:23552
	global_load_lds_dwordx4 v[158:159], off
	s_add_i32 m0, s33, 0x2000
	s_add_u32 s34, s8, 0x40000
	v_lshl_add_u64 v[182:183], s[8:9], 0, v[152:153]
	s_addc_u32 s35, s9, 0
	s_add_i32 s33, s36, s15
	global_load_lds_dwordx4 v[182:183], off
	v_lshl_add_u64 v[230:231], s[34:35], 0, v[148:149]
	s_mov_b32 m0, s33
	v_lshl_add_u64 v[232:233], s[10:11], 0, v[150:151]
	global_load_lds_dwordx4 v[230:231], off
	v_lshl_add_u64 v[230:231], s[34:35], 0, v[152:153]
	s_add_i32 m0, s33, 0x2000
	s_nop 0
	global_load_lds_dwordx4 v[230:231], off
	v_lshl_add_u64 v[230:231], s[10:11], 0, v[146:147]
	s_mov_b32 m0, s16
	s_nop 0
	global_load_lds_dwordx4 v[230:231], off
	s_mov_b32 m0, s17
	s_nop 0
	global_load_lds_dwordx4 v[232:233], off
	s_waitcnt vmcnt(8)
	s_waitcnt lgkmcnt(0)
	s_barrier
; #define PG8_STAGE(bufoff, gbase, voff) do { _Pragma("unroll") for (int _i = 0; _i < 2; ++_i) \
;         __builtin_amdgcn_global_load_lds((const unsigned*)((const char*)(gbase) + (voff)[_i]), (PG8_LAS unsigned*)(lds + (bufoff) + ldsw + _i * 8192), 16, 0, 0); } while (0)
; #define PG8_LDA(dst, b, h) do { _Pragma("unroll") for (int m = 0; m < 4; ++m) _Pragma("unroll") for (int k = 0; k < 2; ++k) dst[m][k] = *(const PG8_LAS bf16x8*)(lds + PG8_SA(b, h) + aoff + m * 2048 + k * 1024); } while (0)
; #define PG8_LDB(dst, b, h) do { _Pragma("unroll") for (int n = 0; n < 2; ++n) _Pragma("unroll") for (int k = 0; k < 2; ++k) dst[n][k] = *(const PG8_LAS bf16x8*)(lds + PG8_SB(b, h) + boff + n * 2048 + k * 1024); } while (0)
; #define PG8_MMA(ai, bj, At, Bt) do { __builtin_amdgcn_s_setprio(1); _Pragma("unroll") for (int m = 0; m < 4; ++m) _Pragma("unroll") for (int n = 0; n < 2; ++n) _Pragma("unroll") for (int k = 0; k < 2; ++k) \
;         acc[ai][bj][m][n] = __builtin_amdgcn_mfma_f32_16x16x32_bf16(Bt[n][k], At[m][k], acc[ai][bj][m][n], 0, 0, 0); __builtin_amdgcn_s_setprio(0); } while (0)
; #define PG8_WAIT_V(n) asm volatile("s_waitcnt vmcnt(" #n ")" ::: "memory")
; #define PG8_WAIT_L(n) asm volatile("s_waitcnt lgkmcnt(" #n ")" ::: "memory")
; #define PG8_BAR __builtin_amdgcn_s_barrier()
; #define PG8_SCHED __builtin_amdgcn_sched_barrier(0)
; template <class Epi, class Sched, bool ALIGN_EPI = false, bool SP2 = false>
; __device__ __forceinline__ void gemm_phase(PG8_LAS unsigned char* lds, const Gemm g, const Sched& S, const Epi& E) {
;     ...
;             PG8_WAIT_V(8); PG8_WAIT_L(0); PG8_BAR; PG8_MMA(1, 0, At, B0); PG8_MMA(1, 1, At, B1); PG8_BAR; PG8_SCHED;
;             PG8_LDB(B0, 1, 0); PG8_LDB(B1, 1, 1); PG8_SCHED; PG8_LDA(At, 1, 0); PG8_STAGE(PG8_SA(0, 1), a2 + hstep, voffA);
;             PG8_WAIT_V(8); PG8_WAIT_L(0); PG8_BAR; PG8_MMA(0, 0, At, B0); PG8_MMA(0, 1, At, B1); PG8_BAR; PG8_SCHED;
	v_mfma_f32_16x16x32_bf16 v[60:63], v[130:133], v[188:191], v[60:63]
	v_mfma_f32_16x16x32_bf16 v[56:59], v[138:141], v[188:191], v[56:59]
	v_mfma_f32_16x16x32_bf16 v[44:47], v[130:133], v[196:199], v[44:47]
	v_mfma_f32_16x16x32_bf16 v[40:43], v[138:141], v[196:199], v[40:43]
	v_mfma_f32_16x16x32_bf16 v[28:31], v[130:133], v[204:207], v[28:31]
	v_mfma_f32_16x16x32_bf16 v[24:27], v[138:141], v[204:207], v[24:27]
	v_mfma_f32_16x16x32_bf16 v[12:15], v[130:133], v[212:215], v[12:15]
	v_mfma_f32_16x16x32_bf16 v[8:11], v[138:141], v[212:215], v[8:11]
	v_mfma_f32_16x16x32_bf16 v[60:63], v[134:137], v[192:195], v[60:63]
	v_mfma_f32_16x16x32_bf16 v[56:59], v[142:145], v[192:195], v[56:59]
	v_mfma_f32_16x16x32_bf16 v[44:47], v[134:137], v[200:203], v[44:47]
	v_mfma_f32_16x16x32_bf16 v[40:43], v[142:145], v[200:203], v[40:43]
	v_mfma_f32_16x16x32_bf16 v[28:31], v[134:137], v[208:211], v[28:31]
	v_mfma_f32_16x16x32_bf16 v[24:27], v[142:145], v[208:211], v[24:27]
	v_mfma_f32_16x16x32_bf16 v[12:15], v[134:137], v[216:219], v[12:15]
	v_mfma_f32_16x16x32_bf16 v[8:11], v[142:145], v[216:219], v[8:11]
	v_mfma_f32_16x16x32_bf16 v[52:55], v[166:169], v[188:191], v[52:55]
	v_mfma_f32_16x16x32_bf16 v[48:51], v[174:177], v[188:191], v[48:51]
	v_mfma_f32_16x16x32_bf16 v[36:39], v[166:169], v[196:199], v[36:39]
	v_mfma_f32_16x16x32_bf16 v[32:35], v[174:177], v[196:199], v[32:35]
	v_mfma_f32_16x16x32_bf16 v[20:23], v[166:169], v[204:207], v[20:23]
	v_mfma_f32_16x16x32_bf16 v[16:19], v[174:177], v[204:207], v[16:19]
	v_mfma_f32_16x16x32_bf16 v[4:7], v[166:169], v[212:215], v[4:7]
	v_mfma_f32_16x16x32_bf16 v[0:3], v[174:177], v[212:215], v[0:3]
	v_mfma_f32_16x16x32_bf16 v[52:55], v[170:173], v[192:195], v[52:55]
	v_mfma_f32_16x16x32_bf16 v[48:51], v[178:181], v[192:195], v[48:51]
	v_mfma_f32_16x16x32_bf16 v[36:39], v[170:173], v[200:203], v[36:39]
	v_mfma_f32_16x16x32_bf16 v[32:35], v[178:181], v[200:203], v[32:35]
	v_mfma_f32_16x16x32_bf16 v[20:23], v[170:173], v[208:211], v[20:23]
	v_mfma_f32_16x16x32_bf16 v[16:19], v[178:181], v[208:211], v[16:19]
	v_mfma_f32_16x16x32_bf16 v[4:7], v[170:173], v[216:219], v[4:7]
	v_mfma_f32_16x16x32_bf16 v[0:3], v[178:181], v[216:219], v[0:3]
	s_barrier
	s_add_i32 s33, 0, 0x18000
	v_add_u32_e32 v64, s33, v161
	s_add_i32 s34, 0, 0x1c000
	ds_read_b128 v[130:133], v64
	ds_read_b128 v[134:137], v64 offset:1024
	ds_read_b128 v[138:141], v64 offset:2048
	ds_read_b128 v[142:145], v64 offset:3072
	v_add_u32_e32 v64, s34, v161
	ds_read_b128 v[166:169], v64
	ds_read_b128 v[170:173], v64 offset:1024
	ds_read_b128 v[174:177], v64 offset:2048
	ds_read_b128 v[178:181], v64 offset:3072
	s_add_u32 s10, s10, 0x40000
	s_addc_u32 s11, s11, 0
	s_mov_b32 m0, s18
	v_lshl_add_u64 v[234:235], s[10:11], 0, v[146:147]
	ds_read_b128 v[188:191], v164 offset:32768
	ds_read_b128 v[192:195], v164 offset:33792
	ds_read_b128 v[196:199], v164 offset:34816
	ds_read_b128 v[200:203], v164 offset:35840
	ds_read_b128 v[204:207], v164 offset:36864
	ds_read_b128 v[208:211], v164 offset:37888
	ds_read_b128 v[212:215], v164 offset:38912
	ds_read_b128 v[216:219], v164 offset:39936
	global_load_lds_dwordx4 v[234:235], off
	v_lshl_add_u64 v[234:235], s[10:11], 0, v[150:151]
	s_mov_b32 m0, s19
	s_nop 0
	global_load_lds_dwordx4 v[234:235], off
	s_waitcnt vmcnt(8)
	s_waitcnt lgkmcnt(0)
	s_barrier
	v_mfma_f32_16x16x32_bf16 v[126:129], v[130:133], v[188:191], v[126:129]
	v_mfma_f32_16x16x32_bf16 v[122:125], v[138:141], v[188:191], v[122:125]
	v_mfma_f32_16x16x32_bf16 v[110:113], v[130:133], v[196:199], v[110:113]
	v_mfma_f32_16x16x32_bf16 v[106:109], v[138:141], v[196:199], v[106:109]
	v_mfma_f32_16x16x32_bf16 v[94:97], v[130:133], v[204:207], v[94:97]
	v_mfma_f32_16x16x32_bf16 v[90:93], v[138:141], v[204:207], v[90:93]
	v_mfma_f32_16x16x32_bf16 v[78:81], v[130:133], v[212:215], v[78:81]
	v_mfma_f32_16x16x32_bf16 v[74:77], v[138:141], v[212:215], v[74:77]
	v_mfma_f32_16x16x32_bf16 v[126:129], v[134:137], v[192:195], v[126:129]
	v_mfma_f32_16x16x32_bf16 v[122:125], v[142:145], v[192:195], v[122:125]
	v_mfma_f32_16x16x32_bf16 v[110:113], v[134:137], v[200:203], v[110:113]
	v_mfma_f32_16x16x32_bf16 v[106:109], v[142:145], v[200:203], v[106:109]
	v_mfma_f32_16x16x32_bf16 v[94:97], v[134:137], v[208:211], v[94:97]
	v_mfma_f32_16x16x32_bf16 v[90:93], v[142:145], v[208:211], v[90:93]
	v_mfma_f32_16x16x32_bf16 v[78:81], v[134:137], v[216:219], v[78:81]
	v_mfma_f32_16x16x32_bf16 v[74:77], v[142:145], v[216:219], v[74:77]
	v_mfma_f32_16x16x32_bf16 v[118:121], v[166:169], v[188:191], v[118:121]
	v_mfma_f32_16x16x32_bf16 v[114:117], v[174:177], v[188:191], v[114:117]
	v_mfma_f32_16x16x32_bf16 v[102:105], v[166:169], v[196:199], v[102:105]
	v_mfma_f32_16x16x32_bf16 v[98:101], v[174:177], v[196:199], v[98:101]
	v_mfma_f32_16x16x32_bf16 v[86:89], v[166:169], v[204:207], v[86:89]
	v_mfma_f32_16x16x32_bf16 v[82:85], v[174:177], v[204:207], v[82:85]
	v_mfma_f32_16x16x32_bf16 v[70:73], v[166:169], v[212:215], v[70:73]
	v_mfma_f32_16x16x32_bf16 v[66:69], v[174:177], v[212:215], v[66:69]
	v_mfma_f32_16x16x32_bf16 v[118:121], v[170:173], v[192:195], v[118:121]
	v_mfma_f32_16x16x32_bf16 v[114:117], v[178:181], v[192:195], v[114:117]
	v_mfma_f32_16x16x32_bf16 v[102:105], v[170:173], v[200:203], v[102:105]
	v_mfma_f32_16x16x32_bf16 v[98:101], v[178:181], v[200:203], v[98:101]
	v_mfma_f32_16x16x32_bf16 v[86:89], v[170:173], v[208:211], v[86:89]
	v_mfma_f32_16x16x32_bf16 v[82:85], v[178:181], v[208:211], v[82:85]
	v_mfma_f32_16x16x32_bf16 v[70:73], v[170:173], v[216:219], v[70:73]
	v_mfma_f32_16x16x32_bf16 v[66:69], v[178:181], v[216:219], v[66:69]
	s_barrier
; #define PG8_STAGE(bufoff, gbase, voff) do { _Pragma("unroll") for (int _i = 0; _i < 2; ++_i) \
;         __builtin_amdgcn_global_load_lds((const unsigned*)((const char*)(gbase) + (voff)[_i]), (PG8_LAS unsigned*)(lds + (bufoff) + ldsw + _i * 8192), 16, 0, 0); } while (0)
; #define PG8_LDA(dst, b, h) do { _Pragma("unroll") for (int m = 0; m < 4; ++m) _Pragma("unroll") for (int k = 0; k < 2; ++k) dst[m][k] = *(const PG8_LAS bf16x8*)(lds + PG8_SA(b, h) + aoff + m * 2048 + k * 1024); } while (0)
; #define PG8_MMA(ai, bj, At, Bt) do { __builtin_amdgcn_s_setprio(1); _Pragma("unroll") for (int m = 0; m < 4; ++m) _Pragma("unroll") for (int n = 0; n < 2; ++n) _Pragma("unroll") for (int k = 0; k < 2; ++k) \
;         acc[ai][bj][m][n] = __builtin_amdgcn_mfma_f32_16x16x32_bf16(Bt[n][k], At[m][k], acc[ai][bj][m][n], 0, 0, 0); __builtin_amdgcn_s_setprio(0); } while (0)
; #define PG8_WAIT_V(n) asm volatile("s_waitcnt vmcnt(" #n ")" ::: "memory")
; #define PG8_WAIT_L(n) asm volatile("s_waitcnt lgkmcnt(" #n ")" ::: "memory")
; #define PG8_BAR __builtin_amdgcn_s_barrier()
; #define PG8_SCHED __builtin_amdgcn_sched_barrier(0)
; template <class Epi, class Sched, bool ALIGN_EPI = false, bool SP2 = false>
; __device__ __forceinline__ void gemm_phase(PG8_LAS unsigned char* lds, const Gemm g, const Sched& S, const Epi& E) {
;     ...
;             PG8_LDA(At, 1, 1); PG8_STAGE(PG8_SB(1, 0), b3, voffB); PG8_STAGE(PG8_SB(1, 1), b3 + hstep, voffB); PG8_STAGE(PG8_SA(1, 0), a3, voffA);
;             PG8_WAIT_V(8); PG8_WAIT_L(0); PG8_BAR; PG8_MMA(1, 0, At, B0); PG8_MMA(1, 1, At, B1); PG8_BAR; PG8_SCHED;
	s_add_i32 s10, s33, s15
	v_lshl_add_u64 v[158:159], v[158:159], 0, s[40:41]
	s_mov_b32 m0, s10
	ds_read_b128 v[188:191], v164 offset:49152
	ds_read_b128 v[192:195], v164 offset:50176
	ds_read_b128 v[196:199], v164 offset:51200
	ds_read_b128 v[200:203], v164 offset:52224
	ds_read_b128 v[204:207], v164 offset:53248
	ds_read_b128 v[208:211], v164 offset:54272
	ds_read_b128 v[212:215], v164 offset:55296
	ds_read_b128 v[216:219], v164 offset:56320
	global_load_lds_dwordx4 v[158:159], off
	s_add_i32 m0, s10, 0x2000
	s_add_u32 s8, s8, 0x40080
	v_lshl_add_u64 v[158:159], v[182:183], 0, s[40:41]
	s_addc_u32 s9, s9, 0
	s_add_i32 s10, s34, s15
	global_load_lds_dwordx4 v[158:159], off
	v_lshl_add_u64 v[158:159], s[8:9], 0, v[148:149]
	s_mov_b32 m0, s10
	s_nop 0
	global_load_lds_dwordx4 v[158:159], off
	v_lshl_add_u64 v[158:159], s[8:9], 0, v[152:153]
	s_add_i32 m0, s10, 0x2000
	s_nop 0
	global_load_lds_dwordx4 v[158:159], off
	v_lshl_add_u64 v[158:159], v[230:231], 0, s[40:41]
	s_mov_b32 m0, s20
	s_nop 0
	global_load_lds_dwordx4 v[158:159], off
	v_lshl_add_u64 v[158:159], v[232:233], 0, s[40:41]
	s_mov_b32 m0, s21
	s_nop 0
	global_load_lds_dwordx4 v[158:159], off
	s_waitcnt vmcnt(8)
	s_waitcnt lgkmcnt(0)
	s_barrier
	v_mfma_f32_16x16x32_bf16 v[60:63], v[130:133], v[188:191], v[60:63]
	v_mfma_f32_16x16x32_bf16 v[56:59], v[138:141], v[188:191], v[56:59]
	v_mfma_f32_16x16x32_bf16 v[44:47], v[130:133], v[196:199], v[44:47]
	v_mfma_f32_16x16x32_bf16 v[40:43], v[138:141], v[196:199], v[40:43]
	v_mfma_f32_16x16x32_bf16 v[28:31], v[130:133], v[204:207], v[28:31]
	v_mfma_f32_16x16x32_bf16 v[24:27], v[138:141], v[204:207], v[24:27]
	v_mfma_f32_16x16x32_bf16 v[12:15], v[130:133], v[212:215], v[12:15]
	v_mfma_f32_16x16x32_bf16 v[8:11], v[138:141], v[212:215], v[8:11]
	v_mfma_f32_16x16x32_bf16 v[60:63], v[134:137], v[192:195], v[60:63]
	v_mfma_f32_16x16x32_bf16 v[56:59], v[142:145], v[192:195], v[56:59]
	v_mfma_f32_16x16x32_bf16 v[44:47], v[134:137], v[200:203], v[44:47]
	v_mfma_f32_16x16x32_bf16 v[40:43], v[142:145], v[200:203], v[40:43]
	v_mfma_f32_16x16x32_bf16 v[28:31], v[134:137], v[208:211], v[28:31]
	v_mfma_f32_16x16x32_bf16 v[24:27], v[142:145], v[208:211], v[24:27]
	v_mfma_f32_16x16x32_bf16 v[12:15], v[134:137], v[216:219], v[12:15]
	v_mfma_f32_16x16x32_bf16 v[8:11], v[142:145], v[216:219], v[8:11]
	v_mfma_f32_16x16x32_bf16 v[52:55], v[166:169], v[188:191], v[52:55]
	v_mfma_f32_16x16x32_bf16 v[48:51], v[174:177], v[188:191], v[48:51]
	v_mfma_f32_16x16x32_bf16 v[36:39], v[166:169], v[196:199], v[36:39]
	v_mfma_f32_16x16x32_bf16 v[32:35], v[174:177], v[196:199], v[32:35]
	v_mfma_f32_16x16x32_bf16 v[20:23], v[166:169], v[204:207], v[20:23]
	v_mfma_f32_16x16x32_bf16 v[16:19], v[174:177], v[204:207], v[16:19]
	v_mfma_f32_16x16x32_bf16 v[4:7], v[166:169], v[212:215], v[4:7]
	v_mfma_f32_16x16x32_bf16 v[0:3], v[174:177], v[212:215], v[0:3]
	v_mfma_f32_16x16x32_bf16 v[52:55], v[170:173], v[192:195], v[52:55]
	v_mfma_f32_16x16x32_bf16 v[48:51], v[178:181], v[192:195], v[48:51]
	v_mfma_f32_16x16x32_bf16 v[36:39], v[170:173], v[200:203], v[36:39]
	v_mfma_f32_16x16x32_bf16 v[32:35], v[178:181], v[200:203], v[32:35]
	v_mfma_f32_16x16x32_bf16 v[20:23], v[170:173], v[208:211], v[20:23]
	v_mfma_f32_16x16x32_bf16 v[16:19], v[178:181], v[208:211], v[16:19]
	v_mfma_f32_16x16x32_bf16 v[4:7], v[170:173], v[216:219], v[4:7]
	v_mfma_f32_16x16x32_bf16 v[0:3], v[178:181], v[216:219], v[0:3]
	s_barrier
	s_add_i32 s29, s29, 2
	s_add_u32 s6, s6, 0x100
	s_addc_u32 s7, s7, 0
	s_add_u32 s27, s27, 0x100
	s_addc_u32 s28, s28, 0
	s_cmp_gt_u32 s29, 13
	s_cbranch_scc0 .LBB0_473
	s_and_b64 vcc, exec, s[62:63]
	s_cbranch_vccz .LBB0_476
	s_barrier
